# m1-m4: + prologue p-copy unrolled (16 loads in flight), weight transposes issue 32 loads before waiting
# baseline (speedup 1.0000x reference)
; #define LAS __attribute__((address_space(3)))
; __device__ __forceinline__ unsigned pk2(float lo, float hi) { f32x2 v = {lo, hi}; bf16x2_t b = __builtin_convertvector(v, bf16x2_t); return __builtin_bit_cast(unsigned, b); }
; __device__ __forceinline__ void transpose_item(const float* W, int K, int N, bf16* WT, int mode, LAS float* scr, int item, int lane) {
;     ...
; #pragma unroll 8
;     for (int i = 0; i < 32; ++i) { const int kk = 2 * i + (lane >> 5); scr[kk * 33 + (lane & 31)] = __builtin_nontemporal_load(W + (size_t)(k0 + kk) * N + n0 + (lane & 31)); }
;     asm volatile("s_waitcnt lgkmcnt(0)" ::: "memory");
;     const int c = lane & 7;
; #pragma unroll
;     for (int j = 0; j < 4; ++j) { const int n = (lane >> 3) + 8 * j; const LAS float* s = scr + (8 * c) * 33 + n;
;         u32x4 o; o.x = pk2(s[0 * 33], s[1 * 33]); o.y = pk2(s[2 * 33], s[3 * 33]); o.z = pk2(s[4 * 33], s[5 * 33]); o.w = pk2(s[6 * 33], s[7 * 33]);
;         *(u32x4*)(WT + (size_t)(r0 + n) * K + k0 + 8 * c) = o; }
;     asm volatile("s_waitcnt lgkmcnt(0)" ::: "memory");
.LBB0_665:
	v_lshl_add_u64 v[74:75], v[40:41], 0, s[10:11]
	v_lshl_add_u64 v[76:77], v[38:39], 0, s[10:11]
	v_lshl_add_u64 v[78:79], v[36:37], 0, s[10:11]
	v_lshl_add_u64 v[80:81], v[34:35], 0, s[10:11]
	v_lshl_add_u64 v[82:83], v[32:33], 0, s[10:11]
	v_lshl_add_u64 v[84:85], v[30:31], 0, s[10:11]
	v_lshl_add_u64 v[86:87], v[28:29], 0, s[10:11]
	v_lshl_add_u64 v[88:89], v[26:27], 0, s[10:11]
	global_load_dword v90, v[74:75], off nt
	global_load_dword v91, v[76:77], off nt
	global_load_dword v92, v[78:79], off nt
	global_load_dword v93, v[80:81], off nt
	global_load_dword v94, v[82:83], off nt
	global_load_dword v95, v[84:85], off nt
	global_load_dword v96, v[86:87], off nt
	global_load_dword v97, v[88:89], off nt
	s_add_u32 s10, s10, 0x10000
	s_addc_u32 s11, s11, 0
	v_lshl_add_u64 v[74:75], v[40:41], 0, s[10:11]
	v_lshl_add_u64 v[76:77], v[38:39], 0, s[10:11]
	v_lshl_add_u64 v[78:79], v[36:37], 0, s[10:11]
	v_lshl_add_u64 v[80:81], v[34:35], 0, s[10:11]
	v_lshl_add_u64 v[82:83], v[32:33], 0, s[10:11]
	v_lshl_add_u64 v[84:85], v[30:31], 0, s[10:11]
	v_lshl_add_u64 v[86:87], v[28:29], 0, s[10:11]
	v_lshl_add_u64 v[88:89], v[26:27], 0, s[10:11]
	global_load_dword v98, v[74:75], off nt
	global_load_dword v99, v[76:77], off nt
	global_load_dword v100, v[78:79], off nt
	global_load_dword v101, v[80:81], off nt
	global_load_dword v102, v[82:83], off nt
	global_load_dword v103, v[84:85], off nt
	global_load_dword v104, v[86:87], off nt
	global_load_dword v105, v[88:89], off nt
	s_add_u32 s10, s10, 0x10000
	s_addc_u32 s11, s11, 0
	v_lshl_add_u64 v[74:75], v[40:41], 0, s[10:11]
	v_lshl_add_u64 v[76:77], v[38:39], 0, s[10:11]
	v_lshl_add_u64 v[78:79], v[36:37], 0, s[10:11]
	v_lshl_add_u64 v[80:81], v[34:35], 0, s[10:11]
	v_lshl_add_u64 v[82:83], v[32:33], 0, s[10:11]
	v_lshl_add_u64 v[84:85], v[30:31], 0, s[10:11]
	v_lshl_add_u64 v[86:87], v[28:29], 0, s[10:11]
	v_lshl_add_u64 v[88:89], v[26:27], 0, s[10:11]
	global_load_dword v106, v[74:75], off nt
	global_load_dword v107, v[76:77], off nt
	global_load_dword v108, v[78:79], off nt
	global_load_dword v109, v[80:81], off nt
	global_load_dword v110, v[82:83], off nt
	global_load_dword v111, v[84:85], off nt
	global_load_dword v112, v[86:87], off nt
	global_load_dword v113, v[88:89], off nt
	s_add_u32 s10, s10, 0x10000
	s_addc_u32 s11, s11, 0
	v_lshl_add_u64 v[74:75], v[40:41], 0, s[10:11]
	v_lshl_add_u64 v[76:77], v[38:39], 0, s[10:11]
	v_lshl_add_u64 v[78:79], v[36:37], 0, s[10:11]
	v_lshl_add_u64 v[80:81], v[34:35], 0, s[10:11]
	v_lshl_add_u64 v[82:83], v[32:33], 0, s[10:11]
	v_lshl_add_u64 v[84:85], v[30:31], 0, s[10:11]
	v_lshl_add_u64 v[86:87], v[28:29], 0, s[10:11]
	v_lshl_add_u64 v[88:89], v[26:27], 0, s[10:11]
	global_load_dword v114, v[74:75], off nt
	global_load_dword v115, v[76:77], off nt
	global_load_dword v116, v[78:79], off nt
	global_load_dword v117, v[80:81], off nt
	global_load_dword v118, v[82:83], off nt
	global_load_dword v119, v[84:85], off nt
	global_load_dword v120, v[86:87], off nt
	global_load_dword v121, v[88:89], off nt
	s_add_u32 s10, s10, 0x10000
	s_addc_u32 s11, s11, 0
	s_waitcnt vmcnt(24)
	v_add_u32_e32 v65, 0x400, v56
	ds_write2_b32 v56, v90, v91 offset1:66
	ds_write2_b32 v56, v92, v93 offset0:132 offset1:198
	ds_write2_b32 v65, v94, v95 offset0:8 offset1:74
	ds_write2_b32 v65, v96, v97 offset0:140 offset1:206
	v_add_u32_e32 v56, 0x840, v56
	s_waitcnt vmcnt(16)
	v_add_u32_e32 v65, 0x400, v56
	ds_write2_b32 v56, v98, v99 offset1:66
	ds_write2_b32 v56, v100, v101 offset0:132 offset1:198
	ds_write2_b32 v65, v102, v103 offset0:8 offset1:74
	ds_write2_b32 v65, v104, v105 offset0:140 offset1:206
	v_add_u32_e32 v56, 0x840, v56
	s_waitcnt vmcnt(8)
	v_add_u32_e32 v65, 0x400, v56
	ds_write2_b32 v56, v106, v107 offset1:66
	ds_write2_b32 v56, v108, v109 offset0:132 offset1:198
	ds_write2_b32 v65, v110, v111 offset0:8 offset1:74
	ds_write2_b32 v65, v112, v113 offset0:140 offset1:206
	v_add_u32_e32 v56, 0x840, v56
	s_waitcnt vmcnt(0)
	v_add_u32_e32 v65, 0x400, v56
	ds_write2_b32 v56, v114, v115 offset1:66
	ds_write2_b32 v56, v116, v117 offset0:132 offset1:198
	ds_write2_b32 v65, v118, v119 offset0:8 offset1:74
	ds_write2_b32 v65, v120, v121 offset0:140 offset1:206
	v_add_u32_e32 v56, 0x840, v56
	s_waitcnt lgkmcnt(0)
	ds_read2_b32 v[30:31], v44 offset0:33 offset1:41
	ds_read2_b32 v[32:33], v44 offset1:8
	ds_read2_b32 v[34:35], v44 offset0:66 offset1:74
	ds_read2_b32 v[36:37], v44 offset0:99 offset1:107
	ds_read2_b32 v[38:39], v44 offset0:132 offset1:140
	ds_read2_b32 v[40:41], v44 offset0:165 offset1:173
	ds_read2_b32 v[56:57], v44 offset0:198 offset1:206
	ds_read2_b32 v[58:59], v44 offset0:231 offset1:239
	s_lshl_b32 s26, s15, 1
	s_waitcnt lgkmcnt(6)
	v_cvt_pk_bf16_f32 v26, v32, v30
	v_or_b32_e32 v30, s13, v43
	v_lshl_add_u64 v[60:61], v[0:1], 0, s[26:27]
	v_lshlrev_b32_e32 v192, 9, v30
	s_waitcnt lgkmcnt(4)
	v_cvt_pk_bf16_f32 v27, v34, v36
	s_waitcnt lgkmcnt(2)
	v_cvt_pk_bf16_f32 v28, v38, v40
	s_waitcnt lgkmcnt(0)
	v_cvt_pk_bf16_f32 v29, v56, v58
	v_lshl_add_u64 v[62:63], v[60:61], 0, v[192:193]
	global_store_dwordx4 v[62:63], v[26:29], off
	v_or_b32_e32 v30, s13, v45
	v_lshlrev_b32_e32 v192, 9, v30
	v_cvt_pk_bf16_f32 v26, v33, v31
	v_cvt_pk_bf16_f32 v27, v35, v37
	v_cvt_pk_bf16_f32 v28, v39, v41
	v_cvt_pk_bf16_f32 v29, v57, v59
	ds_read2_b32 v[32:33], v44 offset0:49 offset1:57
	ds_read2_b32 v[34:35], v44 offset0:16 offset1:24
	ds_read2_b32 v[36:37], v44 offset0:82 offset1:90
	ds_read2_b32 v[38:39], v44 offset0:115 offset1:123
	ds_read2_b32 v[40:41], v44 offset0:148 offset1:156
	ds_read2_b32 v[56:57], v44 offset0:181 offset1:189
	ds_read2_b32 v[58:59], v44 offset0:214 offset1:222
	ds_read2_b32 v[62:63], v44 offset0:247 offset1:255
	v_lshl_add_u64 v[30:31], v[60:61], 0, v[192:193]
	global_store_dwordx4 v[30:31], v[26:29], off
	v_or_b32_e32 v30, s13, v46
	v_lshlrev_b32_e32 v192, 9, v30
	s_waitcnt lgkmcnt(6)
	v_cvt_pk_bf16_f32 v26, v34, v32
	s_waitcnt lgkmcnt(4)
	v_cvt_pk_bf16_f32 v27, v36, v38
	s_waitcnt lgkmcnt(2)
	v_cvt_pk_bf16_f32 v28, v40, v56
	s_waitcnt lgkmcnt(0)
	v_cvt_pk_bf16_f32 v29, v58, v62
	v_lshl_add_u64 v[30:31], v[60:61], 0, v[192:193]
	global_store_dwordx4 v[30:31], v[26:29], off
	v_or_b32_e32 v30, s13, v47
	v_lshlrev_b32_e32 v192, 9, v30
	v_cvt_pk_bf16_f32 v26, v35, v33
	v_cvt_pk_bf16_f32 v27, v37, v39
	v_cvt_pk_bf16_f32 v28, v41, v57
	v_cvt_pk_bf16_f32 v29, v59, v63
	v_lshl_add_u64 v[30:31], v[60:61], 0, v[192:193]
	global_store_dwordx4 v[30:31], v[26:29], off
	s_waitcnt lgkmcnt(0)
	s_mov_b64 s[10:11], 0

; #define LAS __attribute__((address_space(3)))
; __device__ __forceinline__ unsigned pk2(float lo, float hi) { f32x2 v = {lo, hi}; bf16x2_t b = __builtin_convertvector(v, bf16x2_t); return __builtin_bit_cast(unsigned, b); }
; __device__ __forceinline__ void transpose_item(const float* W, int K, int N, bf16* WT, int mode, LAS float* scr, int item, int lane) {
;     ...
; #pragma unroll 8
;     for (int i = 0; i < 32; ++i) { const int kk = 2 * i + (lane >> 5); scr[kk * 33 + (lane & 31)] = __builtin_nontemporal_load(W + (size_t)(k0 + kk) * N + n0 + (lane & 31)); }
;     asm volatile("s_waitcnt lgkmcnt(0)" ::: "memory");
;     const int c = lane & 7;
; #pragma unroll
;     for (int j = 0; j < 4; ++j) { const int n = (lane >> 3) + 8 * j; const LAS float* s = scr + (8 * c) * 33 + n;
;         u32x4 o; o.x = pk2(s[0 * 33], s[1 * 33]); o.y = pk2(s[2 * 33], s[3 * 33]); o.z = pk2(s[4 * 33], s[5 * 33]); o.w = pk2(s[6 * 33], s[7 * 33]);
;         *(u32x4*)(WT + (size_t)(r0 + n) * K + k0 + 8 * c) = o; }
;     asm volatile("s_waitcnt lgkmcnt(0)" ::: "memory");
.LBB0_669:
	v_lshl_add_u64 v[74:75], v[40:41], 0, s[10:11]
	v_lshl_add_u64 v[76:77], v[38:39], 0, s[10:11]
	v_lshl_add_u64 v[78:79], v[36:37], 0, s[10:11]
	v_lshl_add_u64 v[80:81], v[34:35], 0, s[10:11]
	v_lshl_add_u64 v[82:83], v[32:33], 0, s[10:11]
	v_lshl_add_u64 v[84:85], v[30:31], 0, s[10:11]
	v_lshl_add_u64 v[86:87], v[28:29], 0, s[10:11]
	v_lshl_add_u64 v[88:89], v[26:27], 0, s[10:11]
	global_load_dword v90, v[74:75], off nt
	global_load_dword v91, v[76:77], off nt
	global_load_dword v92, v[78:79], off nt
	global_load_dword v93, v[80:81], off nt
	global_load_dword v94, v[82:83], off nt
	global_load_dword v95, v[84:85], off nt
	global_load_dword v96, v[86:87], off nt
	global_load_dword v97, v[88:89], off nt
	s_add_u32 s10, s10, 0x10000
	s_addc_u32 s11, s11, 0
	v_lshl_add_u64 v[74:75], v[40:41], 0, s[10:11]
	v_lshl_add_u64 v[76:77], v[38:39], 0, s[10:11]
	v_lshl_add_u64 v[78:79], v[36:37], 0, s[10:11]
	v_lshl_add_u64 v[80:81], v[34:35], 0, s[10:11]
	v_lshl_add_u64 v[82:83], v[32:33], 0, s[10:11]
	v_lshl_add_u64 v[84:85], v[30:31], 0, s[10:11]
	v_lshl_add_u64 v[86:87], v[28:29], 0, s[10:11]
	v_lshl_add_u64 v[88:89], v[26:27], 0, s[10:11]
	global_load_dword v98, v[74:75], off nt
	global_load_dword v99, v[76:77], off nt
	global_load_dword v100, v[78:79], off nt
	global_load_dword v101, v[80:81], off nt
	global_load_dword v102, v[82:83], off nt
	global_load_dword v103, v[84:85], off nt
	global_load_dword v104, v[86:87], off nt
	global_load_dword v105, v[88:89], off nt
	s_add_u32 s10, s10, 0x10000
	s_addc_u32 s11, s11, 0
	v_lshl_add_u64 v[74:75], v[40:41], 0, s[10:11]
	v_lshl_add_u64 v[76:77], v[38:39], 0, s[10:11]
	v_lshl_add_u64 v[78:79], v[36:37], 0, s[10:11]
	v_lshl_add_u64 v[80:81], v[34:35], 0, s[10:11]
	v_lshl_add_u64 v[82:83], v[32:33], 0, s[10:11]
	v_lshl_add_u64 v[84:85], v[30:31], 0, s[10:11]
	v_lshl_add_u64 v[86:87], v[28:29], 0, s[10:11]
	v_lshl_add_u64 v[88:89], v[26:27], 0, s[10:11]
	global_load_dword v106, v[74:75], off nt
	global_load_dword v107, v[76:77], off nt
	global_load_dword v108, v[78:79], off nt
	global_load_dword v109, v[80:81], off nt
	global_load_dword v110, v[82:83], off nt
	global_load_dword v111, v[84:85], off nt
	global_load_dword v112, v[86:87], off nt
	global_load_dword v113, v[88:89], off nt
	s_add_u32 s10, s10, 0x10000
	s_addc_u32 s11, s11, 0
	v_lshl_add_u64 v[74:75], v[40:41], 0, s[10:11]
	v_lshl_add_u64 v[76:77], v[38:39], 0, s[10:11]
	v_lshl_add_u64 v[78:79], v[36:37], 0, s[10:11]
	v_lshl_add_u64 v[80:81], v[34:35], 0, s[10:11]
	v_lshl_add_u64 v[82:83], v[32:33], 0, s[10:11]
	v_lshl_add_u64 v[84:85], v[30:31], 0, s[10:11]
	v_lshl_add_u64 v[86:87], v[28:29], 0, s[10:11]
	v_lshl_add_u64 v[88:89], v[26:27], 0, s[10:11]
	global_load_dword v114, v[74:75], off nt
	global_load_dword v115, v[76:77], off nt
	global_load_dword v116, v[78:79], off nt
	global_load_dword v117, v[80:81], off nt
	global_load_dword v118, v[82:83], off nt
	global_load_dword v119, v[84:85], off nt
	global_load_dword v120, v[86:87], off nt
	global_load_dword v121, v[88:89], off nt
	s_add_u32 s10, s10, 0x10000
	s_addc_u32 s11, s11, 0
	s_waitcnt vmcnt(24)
	v_add_u32_e32 v65, 0x400, v56
	ds_write2_b32 v56, v90, v91 offset1:66
	ds_write2_b32 v56, v92, v93 offset0:132 offset1:198
	ds_write2_b32 v65, v94, v95 offset0:8 offset1:74
	ds_write2_b32 v65, v96, v97 offset0:140 offset1:206
	v_add_u32_e32 v56, 0x840, v56
	s_waitcnt vmcnt(16)
	v_add_u32_e32 v65, 0x400, v56
	ds_write2_b32 v56, v98, v99 offset1:66
	ds_write2_b32 v56, v100, v101 offset0:132 offset1:198
	ds_write2_b32 v65, v102, v103 offset0:8 offset1:74
	ds_write2_b32 v65, v104, v105 offset0:140 offset1:206
	v_add_u32_e32 v56, 0x840, v56
	s_waitcnt vmcnt(8)
	v_add_u32_e32 v65, 0x400, v56
	ds_write2_b32 v56, v106, v107 offset1:66
	ds_write2_b32 v56, v108, v109 offset0:132 offset1:198
	ds_write2_b32 v65, v110, v111 offset0:8 offset1:74
	ds_write2_b32 v65, v112, v113 offset0:140 offset1:206
	v_add_u32_e32 v56, 0x840, v56
	s_waitcnt vmcnt(0)
	v_add_u32_e32 v65, 0x400, v56
	ds_write2_b32 v56, v114, v115 offset1:66
	ds_write2_b32 v56, v116, v117 offset0:132 offset1:198
	ds_write2_b32 v65, v118, v119 offset0:8 offset1:74
	ds_write2_b32 v65, v120, v121 offset0:140 offset1:206
	v_add_u32_e32 v56, 0x840, v56
	s_waitcnt lgkmcnt(0)
	ds_read2_b32 v[30:31], v44 offset0:33 offset1:41
	ds_read2_b32 v[32:33], v44 offset1:8
	ds_read2_b32 v[34:35], v44 offset0:66 offset1:74
	ds_read2_b32 v[36:37], v44 offset0:99 offset1:107
	ds_read2_b32 v[38:39], v44 offset0:132 offset1:140
	ds_read2_b32 v[40:41], v44 offset0:165 offset1:173
	ds_read2_b32 v[56:57], v44 offset0:198 offset1:206
	ds_read2_b32 v[58:59], v44 offset0:231 offset1:239
	s_add_i32 s14, s14, 0x1b500
	s_and_b32 s10, s14, 0x1ffc0
	s_lshl_b32 s26, s10, 1
	s_waitcnt lgkmcnt(6)
	v_cvt_pk_bf16_f32 v26, v32, v30
	v_or_b32_e32 v30, s13, v43
	v_lshl_add_u64 v[60:61], v[2:3], 0, s[26:27]
	v_lshlrev_b32_e32 v192, 11, v30
	s_waitcnt lgkmcnt(4)
	v_cvt_pk_bf16_f32 v27, v34, v36
	s_waitcnt lgkmcnt(2)
	v_cvt_pk_bf16_f32 v28, v38, v40
	s_waitcnt lgkmcnt(0)
	v_cvt_pk_bf16_f32 v29, v56, v58
	v_lshl_add_u64 v[62:63], v[60:61], 0, v[192:193]
	global_store_dwordx4 v[62:63], v[26:29], off
	v_or_b32_e32 v30, s13, v45
	v_lshlrev_b32_e32 v192, 11, v30
	v_cvt_pk_bf16_f32 v26, v33, v31
	v_cvt_pk_bf16_f32 v27, v35, v37
	v_cvt_pk_bf16_f32 v28, v39, v41
	v_cvt_pk_bf16_f32 v29, v57, v59
	ds_read2_b32 v[32:33], v44 offset0:49 offset1:57
	ds_read2_b32 v[34:35], v44 offset0:16 offset1:24
	ds_read2_b32 v[36:37], v44 offset0:82 offset1:90
	ds_read2_b32 v[38:39], v44 offset0:115 offset1:123
	ds_read2_b32 v[40:41], v44 offset0:148 offset1:156
	ds_read2_b32 v[56:57], v44 offset0:181 offset1:189
	ds_read2_b32 v[58:59], v44 offset0:214 offset1:222
	ds_read2_b32 v[62:63], v44 offset0:247 offset1:255
	v_lshl_add_u64 v[30:31], v[60:61], 0, v[192:193]
	global_store_dwordx4 v[30:31], v[26:29], off
	v_or_b32_e32 v30, s13, v46
	v_lshlrev_b32_e32 v192, 11, v30
	s_waitcnt lgkmcnt(6)
	v_cvt_pk_bf16_f32 v26, v34, v32
	s_waitcnt lgkmcnt(4)
	v_cvt_pk_bf16_f32 v27, v36, v38
	s_waitcnt lgkmcnt(2)
	v_cvt_pk_bf16_f32 v28, v40, v56
	s_waitcnt lgkmcnt(0)
	v_cvt_pk_bf16_f32 v29, v58, v62
	v_lshl_add_u64 v[30:31], v[60:61], 0, v[192:193]
	global_store_dwordx4 v[30:31], v[26:29], off
	v_or_b32_e32 v30, s13, v47
	v_lshlrev_b32_e32 v192, 11, v30
	v_cvt_pk_bf16_f32 v26, v35, v33
	v_cvt_pk_bf16_f32 v27, v37, v39
	v_cvt_pk_bf16_f32 v28, v41, v57
	v_cvt_pk_bf16_f32 v29, v59, v63
	v_lshl_add_u64 v[30:31], v[60:61], 0, v[192:193]
	global_store_dwordx4 v[30:31], v[26:29], off
	s_waitcnt lgkmcnt(0)

; #define LAS __attribute__((address_space(3)))
; __device__ __forceinline__ unsigned pk2(float lo, float hi) { f32x2 v = {lo, hi}; bf16x2_t b = __builtin_convertvector(v, bf16x2_t); return __builtin_bit_cast(unsigned, b); }
; __device__ __forceinline__ void transpose_item(const float* W, int K, int N, bf16* WT, int mode, LAS float* scr, int item, int lane) {
;     ...
; #pragma unroll 8
;     for (int i = 0; i < 32; ++i) { const int kk = 2 * i + (lane >> 5); scr[kk * 33 + (lane & 31)] = __builtin_nontemporal_load(W + (size_t)(k0 + kk) * N + n0 + (lane & 31)); }
;     asm volatile("s_waitcnt lgkmcnt(0)" ::: "memory");
;     const int c = lane & 7;
; #pragma unroll
;     for (int j = 0; j < 4; ++j) { const int n = (lane >> 3) + 8 * j; const LAS float* s = scr + (8 * c) * 33 + n;
;         u32x4 o; o.x = pk2(s[0 * 33], s[1 * 33]); o.y = pk2(s[2 * 33], s[3 * 33]); o.z = pk2(s[4 * 33], s[5 * 33]); o.w = pk2(s[6 * 33], s[7 * 33]);
;         *(u32x4*)(WT + (size_t)(r0 + n) * K + k0 + 8 * c) = o; }
;     asm volatile("s_waitcnt lgkmcnt(0)" ::: "memory");
.LBB0_674:
	v_lshl_add_u64 v[74:75], v[40:41], 0, s[10:11]
	v_lshl_add_u64 v[76:77], v[38:39], 0, s[10:11]
	v_lshl_add_u64 v[78:79], v[36:37], 0, s[10:11]
	v_lshl_add_u64 v[80:81], v[34:35], 0, s[10:11]
	v_lshl_add_u64 v[82:83], v[32:33], 0, s[10:11]
	v_lshl_add_u64 v[84:85], v[30:31], 0, s[10:11]
	v_lshl_add_u64 v[86:87], v[28:29], 0, s[10:11]
	v_lshl_add_u64 v[88:89], v[26:27], 0, s[10:11]
	global_load_dword v90, v[74:75], off nt
	global_load_dword v91, v[76:77], off nt
	global_load_dword v92, v[78:79], off nt
	global_load_dword v93, v[80:81], off nt
	global_load_dword v94, v[82:83], off nt
	global_load_dword v95, v[84:85], off nt
	global_load_dword v96, v[86:87], off nt
	global_load_dword v97, v[88:89], off nt
	s_add_u32 s10, s10, 0x10000
	s_addc_u32 s11, s11, 0
	v_lshl_add_u64 v[74:75], v[40:41], 0, s[10:11]
	v_lshl_add_u64 v[76:77], v[38:39], 0, s[10:11]
	v_lshl_add_u64 v[78:79], v[36:37], 0, s[10:11]
	v_lshl_add_u64 v[80:81], v[34:35], 0, s[10:11]
	v_lshl_add_u64 v[82:83], v[32:33], 0, s[10:11]
	v_lshl_add_u64 v[84:85], v[30:31], 0, s[10:11]
	v_lshl_add_u64 v[86:87], v[28:29], 0, s[10:11]
	v_lshl_add_u64 v[88:89], v[26:27], 0, s[10:11]
	global_load_dword v98, v[74:75], off nt
	global_load_dword v99, v[76:77], off nt
	global_load_dword v100, v[78:79], off nt
	global_load_dword v101, v[80:81], off nt
	global_load_dword v102, v[82:83], off nt
	global_load_dword v103, v[84:85], off nt
	global_load_dword v104, v[86:87], off nt
	global_load_dword v105, v[88:89], off nt
	s_add_u32 s10, s10, 0x10000
	s_addc_u32 s11, s11, 0
	v_lshl_add_u64 v[74:75], v[40:41], 0, s[10:11]
	v_lshl_add_u64 v[76:77], v[38:39], 0, s[10:11]
	v_lshl_add_u64 v[78:79], v[36:37], 0, s[10:11]
	v_lshl_add_u64 v[80:81], v[34:35], 0, s[10:11]
	v_lshl_add_u64 v[82:83], v[32:33], 0, s[10:11]
	v_lshl_add_u64 v[84:85], v[30:31], 0, s[10:11]
	v_lshl_add_u64 v[86:87], v[28:29], 0, s[10:11]
	v_lshl_add_u64 v[88:89], v[26:27], 0, s[10:11]
	global_load_dword v106, v[74:75], off nt
	global_load_dword v107, v[76:77], off nt
	global_load_dword v108, v[78:79], off nt
	global_load_dword v109, v[80:81], off nt
	global_load_dword v110, v[82:83], off nt
	global_load_dword v111, v[84:85], off nt
	global_load_dword v112, v[86:87], off nt
	global_load_dword v113, v[88:89], off nt
	s_add_u32 s10, s10, 0x10000
	s_addc_u32 s11, s11, 0
	v_lshl_add_u64 v[74:75], v[40:41], 0, s[10:11]
	v_lshl_add_u64 v[76:77], v[38:39], 0, s[10:11]
	v_lshl_add_u64 v[78:79], v[36:37], 0, s[10:11]
	v_lshl_add_u64 v[80:81], v[34:35], 0, s[10:11]
	v_lshl_add_u64 v[82:83], v[32:33], 0, s[10:11]
	v_lshl_add_u64 v[84:85], v[30:31], 0, s[10:11]
	v_lshl_add_u64 v[86:87], v[28:29], 0, s[10:11]
	v_lshl_add_u64 v[88:89], v[26:27], 0, s[10:11]
	global_load_dword v114, v[74:75], off nt
	global_load_dword v115, v[76:77], off nt
	global_load_dword v116, v[78:79], off nt
	global_load_dword v117, v[80:81], off nt
	global_load_dword v118, v[82:83], off nt
	global_load_dword v119, v[84:85], off nt
	global_load_dword v120, v[86:87], off nt
	global_load_dword v121, v[88:89], off nt
	s_add_u32 s10, s10, 0x10000
	s_addc_u32 s11, s11, 0
	s_waitcnt vmcnt(24)
	v_add_u32_e32 v65, 0x400, v56
	ds_write2_b32 v56, v90, v91 offset1:66
	ds_write2_b32 v56, v92, v93 offset0:132 offset1:198
	ds_write2_b32 v65, v94, v95 offset0:8 offset1:74
	ds_write2_b32 v65, v96, v97 offset0:140 offset1:206
	v_add_u32_e32 v56, 0x840, v56
	s_waitcnt vmcnt(16)
	v_add_u32_e32 v65, 0x400, v56
	ds_write2_b32 v56, v98, v99 offset1:66
	ds_write2_b32 v56, v100, v101 offset0:132 offset1:198
	ds_write2_b32 v65, v102, v103 offset0:8 offset1:74
	ds_write2_b32 v65, v104, v105 offset0:140 offset1:206
	v_add_u32_e32 v56, 0x840, v56
	s_waitcnt vmcnt(8)
	v_add_u32_e32 v65, 0x400, v56
	ds_write2_b32 v56, v106, v107 offset1:66
	ds_write2_b32 v56, v108, v109 offset0:132 offset1:198
	ds_write2_b32 v65, v110, v111 offset0:8 offset1:74
	ds_write2_b32 v65, v112, v113 offset0:140 offset1:206
	v_add_u32_e32 v56, 0x840, v56
	s_waitcnt vmcnt(0)
	v_add_u32_e32 v65, 0x400, v56
	ds_write2_b32 v56, v114, v115 offset1:66
	ds_write2_b32 v56, v116, v117 offset0:132 offset1:198
	ds_write2_b32 v65, v118, v119 offset0:8 offset1:74
	ds_write2_b32 v65, v120, v121 offset0:140 offset1:206
	v_add_u32_e32 v56, 0x840, v56
	s_waitcnt lgkmcnt(0)
	s_lshl_b32 s10, s19, 1
	s_lshl_b32 s11, s19, 5
	ds_read2_b32 v[30:31], v44 offset0:33 offset1:41
	ds_read2_b32 v[32:33], v44 offset1:8
	ds_read2_b32 v[34:35], v44 offset0:66 offset1:74
	ds_read2_b32 v[36:37], v44 offset0:99 offset1:107
	ds_read2_b32 v[38:39], v44 offset0:132 offset1:140
	ds_read2_b32 v[40:41], v44 offset0:165 offset1:173
	ds_read2_b32 v[56:57], v44 offset0:198 offset1:206
	ds_read2_b32 v[58:59], v44 offset0:231 offset1:239
	s_add_i32 s10, s10, 0x1c000
	s_and_b32 s11, s11, 0x3e0
	s_and_b32 s10, s10, 0x1ffc0
	s_waitcnt lgkmcnt(6)
	v_cvt_pk_bf16_f32 v26, v32, v30
	v_or_b32_e32 v30, s11, v43
	s_lshl_b32 s26, s10, 1
	v_mul_u32_u24_e32 v30, 0xb00, v30
	v_lshl_add_u64 v[60:61], v[4:5], 0, s[26:27]
	v_lshlrev_b32_e32 v192, 1, v30
	s_waitcnt lgkmcnt(4)
	v_cvt_pk_bf16_f32 v27, v34, v36
	s_waitcnt lgkmcnt(2)
	v_cvt_pk_bf16_f32 v28, v38, v40
	s_waitcnt lgkmcnt(0)
	v_cvt_pk_bf16_f32 v29, v56, v58
	v_lshl_add_u64 v[62:63], v[60:61], 0, v[192:193]
	v_or_b32_e32 v30, s11, v45
	global_store_dwordx4 v[62:63], v[26:29], off
	v_mul_u32_u24_e32 v30, 0xb00, v30
	v_lshlrev_b32_e32 v192, 1, v30
	v_cvt_pk_bf16_f32 v26, v33, v31
	v_cvt_pk_bf16_f32 v27, v35, v37
	v_cvt_pk_bf16_f32 v28, v39, v41
	v_cvt_pk_bf16_f32 v29, v57, v59
	ds_read2_b32 v[32:33], v44 offset0:16 offset1:24
	ds_read2_b32 v[34:35], v44 offset0:49 offset1:57
	ds_read2_b32 v[36:37], v44 offset0:82 offset1:90
	ds_read2_b32 v[38:39], v44 offset0:115 offset1:123
	ds_read2_b32 v[40:41], v44 offset0:148 offset1:156
	ds_read2_b32 v[56:57], v44 offset0:181 offset1:189
	ds_read2_b32 v[58:59], v44 offset0:214 offset1:222
	ds_read2_b32 v[62:63], v44 offset0:247 offset1:255
	v_lshl_add_u64 v[30:31], v[60:61], 0, v[192:193]
	global_store_dwordx4 v[30:31], v[26:29], off
	v_or_b32_e32 v30, s11, v46
	v_mul_u32_u24_e32 v30, 0xb00, v30
	v_lshlrev_b32_e32 v192, 1, v30
	s_waitcnt lgkmcnt(6)
	v_cvt_pk_bf16_f32 v26, v32, v34
	s_waitcnt lgkmcnt(4)
	v_cvt_pk_bf16_f32 v27, v36, v38
	s_waitcnt lgkmcnt(2)
	v_cvt_pk_bf16_f32 v28, v40, v56
	s_waitcnt lgkmcnt(0)
	v_cvt_pk_bf16_f32 v29, v58, v62
	v_lshl_add_u64 v[30:31], v[60:61], 0, v[192:193]
	global_store_dwordx4 v[30:31], v[26:29], off
	v_or_b32_e32 v30, s11, v47
	v_mul_u32_u24_e32 v30, 0xb00, v30
	v_lshlrev_b32_e32 v192, 1, v30
	v_cvt_pk_bf16_f32 v26, v33, v35
	v_cvt_pk_bf16_f32 v27, v37, v39
	v_cvt_pk_bf16_f32 v28, v41, v57
	v_cvt_pk_bf16_f32 v29, v59, v63
	v_lshl_add_u64 v[30:31], v[60:61], 0, v[192:193]
	global_store_dwordx4 v[30:31], v[26:29], off
	s_waitcnt lgkmcnt(0)

; #define LAS __attribute__((address_space(3)))
; __device__ __forceinline__ unsigned pk2(float lo, float hi) { f32x2 v = {lo, hi}; bf16x2_t b = __builtin_convertvector(v, bf16x2_t); return __builtin_bit_cast(unsigned, b); }
; __device__ __forceinline__ void transpose_item(const float* W, int K, int N, bf16* WT, int mode, LAS float* scr, int item, int lane) {
;     ...
; #pragma unroll 8
;     for (int i = 0; i < 32; ++i) { const int kk = 2 * i + (lane >> 5); scr[kk * 33 + (lane & 31)] = __builtin_nontemporal_load(W + (size_t)(k0 + kk) * N + n0 + (lane & 31)); }
;     asm volatile("s_waitcnt lgkmcnt(0)" ::: "memory");
;     const int c = lane & 7;
; #pragma unroll
;     for (int j = 0; j < 4; ++j) { const int n = (lane >> 3) + 8 * j; const LAS float* s = scr + (8 * c) * 33 + n;
;         u32x4 o; o.x = pk2(s[0 * 33], s[1 * 33]); o.y = pk2(s[2 * 33], s[3 * 33]); o.z = pk2(s[4 * 33], s[5 * 33]); o.w = pk2(s[6 * 33], s[7 * 33]);
;         *(u32x4*)(WT + (size_t)(r0 + n) * K + k0 + 8 * c) = o; }
;     asm volatile("s_waitcnt lgkmcnt(0)" ::: "memory");
.LBB0_679:
	v_lshl_add_u64 v[74:75], v[40:41], 0, s[10:11]
	v_lshl_add_u64 v[76:77], v[38:39], 0, s[10:11]
	v_lshl_add_u64 v[78:79], v[36:37], 0, s[10:11]
	v_lshl_add_u64 v[80:81], v[34:35], 0, s[10:11]
	v_lshl_add_u64 v[82:83], v[32:33], 0, s[10:11]
	v_lshl_add_u64 v[84:85], v[30:31], 0, s[10:11]
	v_lshl_add_u64 v[86:87], v[28:29], 0, s[10:11]
	v_lshl_add_u64 v[88:89], v[26:27], 0, s[10:11]
	global_load_dword v90, v[74:75], off nt
	global_load_dword v91, v[76:77], off nt
	global_load_dword v92, v[78:79], off nt
	global_load_dword v93, v[80:81], off nt
	global_load_dword v94, v[82:83], off nt
	global_load_dword v95, v[84:85], off nt
	global_load_dword v96, v[86:87], off nt
	global_load_dword v97, v[88:89], off nt
	s_add_u32 s10, s10, 0x2c000
	s_addc_u32 s11, s11, 0
	v_lshl_add_u64 v[74:75], v[40:41], 0, s[10:11]
	v_lshl_add_u64 v[76:77], v[38:39], 0, s[10:11]
	v_lshl_add_u64 v[78:79], v[36:37], 0, s[10:11]
	v_lshl_add_u64 v[80:81], v[34:35], 0, s[10:11]
	v_lshl_add_u64 v[82:83], v[32:33], 0, s[10:11]
	v_lshl_add_u64 v[84:85], v[30:31], 0, s[10:11]
	v_lshl_add_u64 v[86:87], v[28:29], 0, s[10:11]
	v_lshl_add_u64 v[88:89], v[26:27], 0, s[10:11]
	global_load_dword v98, v[74:75], off nt
	global_load_dword v99, v[76:77], off nt
	global_load_dword v100, v[78:79], off nt
	global_load_dword v101, v[80:81], off nt
	global_load_dword v102, v[82:83], off nt
	global_load_dword v103, v[84:85], off nt
	global_load_dword v104, v[86:87], off nt
	global_load_dword v105, v[88:89], off nt
	s_add_u32 s10, s10, 0x2c000
	s_addc_u32 s11, s11, 0
	v_lshl_add_u64 v[74:75], v[40:41], 0, s[10:11]
	v_lshl_add_u64 v[76:77], v[38:39], 0, s[10:11]
	v_lshl_add_u64 v[78:79], v[36:37], 0, s[10:11]
	v_lshl_add_u64 v[80:81], v[34:35], 0, s[10:11]
	v_lshl_add_u64 v[82:83], v[32:33], 0, s[10:11]
	v_lshl_add_u64 v[84:85], v[30:31], 0, s[10:11]
	v_lshl_add_u64 v[86:87], v[28:29], 0, s[10:11]
	v_lshl_add_u64 v[88:89], v[26:27], 0, s[10:11]
	global_load_dword v106, v[74:75], off nt
	global_load_dword v107, v[76:77], off nt
	global_load_dword v108, v[78:79], off nt
	global_load_dword v109, v[80:81], off nt
	global_load_dword v110, v[82:83], off nt
	global_load_dword v111, v[84:85], off nt
	global_load_dword v112, v[86:87], off nt
	global_load_dword v113, v[88:89], off nt
	s_add_u32 s10, s10, 0x2c000
	s_addc_u32 s11, s11, 0
	v_lshl_add_u64 v[74:75], v[40:41], 0, s[10:11]
	v_lshl_add_u64 v[76:77], v[38:39], 0, s[10:11]
	v_lshl_add_u64 v[78:79], v[36:37], 0, s[10:11]
	v_lshl_add_u64 v[80:81], v[34:35], 0, s[10:11]
	v_lshl_add_u64 v[82:83], v[32:33], 0, s[10:11]
	v_lshl_add_u64 v[84:85], v[30:31], 0, s[10:11]
	v_lshl_add_u64 v[86:87], v[28:29], 0, s[10:11]
	v_lshl_add_u64 v[88:89], v[26:27], 0, s[10:11]
	global_load_dword v114, v[74:75], off nt
	global_load_dword v115, v[76:77], off nt
	global_load_dword v116, v[78:79], off nt
	global_load_dword v117, v[80:81], off nt
	global_load_dword v118, v[82:83], off nt
	global_load_dword v119, v[84:85], off nt
	global_load_dword v120, v[86:87], off nt
	global_load_dword v121, v[88:89], off nt
	s_add_u32 s10, s10, 0x2c000
	s_addc_u32 s11, s11, 0
	s_waitcnt vmcnt(24)
	v_add_u32_e32 v65, 0x400, v56
	ds_write2_b32 v56, v90, v91 offset1:66
	ds_write2_b32 v56, v92, v93 offset0:132 offset1:198
	ds_write2_b32 v65, v94, v95 offset0:8 offset1:74
	ds_write2_b32 v65, v96, v97 offset0:140 offset1:206
	v_add_u32_e32 v56, 0x840, v56
	s_waitcnt vmcnt(16)
	v_add_u32_e32 v65, 0x400, v56
	ds_write2_b32 v56, v98, v99 offset1:66
	ds_write2_b32 v56, v100, v101 offset0:132 offset1:198
	ds_write2_b32 v65, v102, v103 offset0:8 offset1:74
	ds_write2_b32 v65, v104, v105 offset0:140 offset1:206
	v_add_u32_e32 v56, 0x840, v56
	s_waitcnt vmcnt(8)
	v_add_u32_e32 v65, 0x400, v56
	ds_write2_b32 v56, v106, v107 offset1:66
	ds_write2_b32 v56, v108, v109 offset0:132 offset1:198
	ds_write2_b32 v65, v110, v111 offset0:8 offset1:74
	ds_write2_b32 v65, v112, v113 offset0:140 offset1:206
	v_add_u32_e32 v56, 0x840, v56
	s_waitcnt vmcnt(0)
	v_add_u32_e32 v65, 0x400, v56
	ds_write2_b32 v56, v114, v115 offset1:66
	ds_write2_b32 v56, v116, v117 offset0:132 offset1:198
	ds_write2_b32 v65, v118, v119 offset0:8 offset1:74
	ds_write2_b32 v65, v120, v121 offset0:140 offset1:206
	v_add_u32_e32 v56, 0x840, v56
	s_lshl_b32 s11, s14, 6
	s_waitcnt lgkmcnt(0)
	s_and_b32 s10, s15, 0x60
	s_and_b32 s11, s11, 0x1f00
	ds_read2_b32 v[30:31], v44 offset0:33 offset1:41
	ds_read2_b32 v[32:33], v44 offset1:8
	ds_read2_b32 v[34:35], v44 offset0:66 offset1:74
	ds_read2_b32 v[36:37], v44 offset0:99 offset1:107
	ds_read2_b32 v[38:39], v44 offset0:132 offset1:140
	ds_read2_b32 v[40:41], v44 offset0:165 offset1:173
	ds_read2_b32 v[56:57], v44 offset0:198 offset1:206
	ds_read2_b32 v[58:59], v44 offset0:231 offset1:239
	s_or_b32 s10, s10, s11
	s_bitset1_b32 s10, 7
	s_and_b32 s11, 0xffff, s13
	s_lshl_b32 s26, s11, 1
	s_waitcnt lgkmcnt(6)
	v_cvt_pk_bf16_f32 v26, v32, v30
	v_or_b32_e32 v30, s10, v43
	v_lshl_add_u64 v[60:61], v[6:7], 0, s[26:27]
	v_lshlrev_b32_e32 v192, 11, v30
	s_waitcnt lgkmcnt(4)
	v_cvt_pk_bf16_f32 v27, v34, v36
	s_waitcnt lgkmcnt(2)
	v_cvt_pk_bf16_f32 v28, v38, v40
	s_waitcnt lgkmcnt(0)
	v_cvt_pk_bf16_f32 v29, v56, v58
	v_lshl_add_u64 v[62:63], v[60:61], 0, v[192:193]
	global_store_dwordx4 v[62:63], v[26:29], off
	v_or_b32_e32 v30, s10, v45
	v_lshlrev_b32_e32 v192, 11, v30
	v_cvt_pk_bf16_f32 v26, v33, v31
	v_cvt_pk_bf16_f32 v27, v35, v37
	v_cvt_pk_bf16_f32 v28, v39, v41
	v_cvt_pk_bf16_f32 v29, v57, v59
	ds_read2_b32 v[32:33], v44 offset0:49 offset1:57
	ds_read2_b32 v[34:35], v44 offset0:16 offset1:24
	ds_read2_b32 v[36:37], v44 offset0:82 offset1:90
	ds_read2_b32 v[38:39], v44 offset0:115 offset1:123
	ds_read2_b32 v[40:41], v44 offset0:148 offset1:156
	ds_read2_b32 v[56:57], v44 offset0:181 offset1:189
	ds_read2_b32 v[58:59], v44 offset0:214 offset1:222
	ds_read2_b32 v[62:63], v44 offset0:247 offset1:255
	v_lshl_add_u64 v[30:31], v[60:61], 0, v[192:193]
	global_store_dwordx4 v[30:31], v[26:29], off
	v_or_b32_e32 v30, s10, v46
	v_lshlrev_b32_e32 v192, 11, v30
	s_waitcnt lgkmcnt(6)
	v_cvt_pk_bf16_f32 v26, v34, v32
	s_waitcnt lgkmcnt(4)
	v_cvt_pk_bf16_f32 v27, v36, v38
	s_waitcnt lgkmcnt(2)
	v_cvt_pk_bf16_f32 v28, v40, v56
	s_waitcnt lgkmcnt(0)
	v_cvt_pk_bf16_f32 v29, v58, v62
	v_lshl_add_u64 v[30:31], v[60:61], 0, v[192:193]
	global_store_dwordx4 v[30:31], v[26:29], off
	v_or_b32_e32 v30, s10, v47
	v_lshlrev_b32_e32 v192, 11, v30
	v_cvt_pk_bf16_f32 v26, v35, v33
	v_cvt_pk_bf16_f32 v27, v37, v39
	v_cvt_pk_bf16_f32 v28, v41, v57
	v_cvt_pk_bf16_f32 v29, v59, v63
	v_lshl_add_u64 v[30:31], v[60:61], 0, v[192:193]
	global_store_dwordx4 v[30:31], v[26:29], off
	s_waitcnt lgkmcnt(0)

; #define LAS __attribute__((address_space(3)))
; __device__ __forceinline__ unsigned pk2(float lo, float hi) { f32x2 v = {lo, hi}; bf16x2_t b = __builtin_convertvector(v, bf16x2_t); return __builtin_bit_cast(unsigned, b); }
; __device__ __forceinline__ void transpose_item(const float* W, int K, int N, bf16* WT, int mode, LAS float* scr, int item, int lane) {
;     ...
; #pragma unroll 8
;     for (int i = 0; i < 32; ++i) { const int kk = 2 * i + (lane >> 5); scr[kk * 33 + (lane & 31)] = __builtin_nontemporal_load(W + (size_t)(k0 + kk) * N + n0 + (lane & 31)); }
;     asm volatile("s_waitcnt lgkmcnt(0)" ::: "memory");
;     const int c = lane & 7;
; #pragma unroll
;     for (int j = 0; j < 4; ++j) { const int n = (lane >> 3) + 8 * j; const LAS float* s = scr + (8 * c) * 33 + n;
;         u32x4 o; o.x = pk2(s[0 * 33], s[1 * 33]); o.y = pk2(s[2 * 33], s[3 * 33]); o.z = pk2(s[4 * 33], s[5 * 33]); o.w = pk2(s[6 * 33], s[7 * 33]);
;         *(u32x4*)(WT + (size_t)(r0 + n) * K + k0 + 8 * c) = o; }
;     asm volatile("s_waitcnt lgkmcnt(0)" ::: "memory");
.LBB0_684:
	v_lshl_add_u64 v[74:75], v[40:41], 0, s[10:11]
	v_lshl_add_u64 v[76:77], v[38:39], 0, s[10:11]
	v_lshl_add_u64 v[78:79], v[36:37], 0, s[10:11]
	v_lshl_add_u64 v[80:81], v[34:35], 0, s[10:11]
	v_lshl_add_u64 v[82:83], v[32:33], 0, s[10:11]
	v_lshl_add_u64 v[84:85], v[30:31], 0, s[10:11]
	v_lshl_add_u64 v[86:87], v[28:29], 0, s[10:11]
	v_lshl_add_u64 v[88:89], v[26:27], 0, s[10:11]
	global_load_dword v90, v[74:75], off nt
	global_load_dword v91, v[76:77], off nt
	global_load_dword v92, v[78:79], off nt
	global_load_dword v93, v[80:81], off nt
	global_load_dword v94, v[82:83], off nt
	global_load_dword v95, v[84:85], off nt
	global_load_dword v96, v[86:87], off nt
	global_load_dword v97, v[88:89], off nt
	s_add_u32 s10, s10, 0x2c000
	s_addc_u32 s11, s11, 0
	v_lshl_add_u64 v[74:75], v[40:41], 0, s[10:11]
	v_lshl_add_u64 v[76:77], v[38:39], 0, s[10:11]
	v_lshl_add_u64 v[78:79], v[36:37], 0, s[10:11]
	v_lshl_add_u64 v[80:81], v[34:35], 0, s[10:11]
	v_lshl_add_u64 v[82:83], v[32:33], 0, s[10:11]
	v_lshl_add_u64 v[84:85], v[30:31], 0, s[10:11]
	v_lshl_add_u64 v[86:87], v[28:29], 0, s[10:11]
	v_lshl_add_u64 v[88:89], v[26:27], 0, s[10:11]
	global_load_dword v98, v[74:75], off nt
	global_load_dword v99, v[76:77], off nt
	global_load_dword v100, v[78:79], off nt
	global_load_dword v101, v[80:81], off nt
	global_load_dword v102, v[82:83], off nt
	global_load_dword v103, v[84:85], off nt
	global_load_dword v104, v[86:87], off nt
	global_load_dword v105, v[88:89], off nt
	s_add_u32 s10, s10, 0x2c000
	s_addc_u32 s11, s11, 0
	v_lshl_add_u64 v[74:75], v[40:41], 0, s[10:11]
	v_lshl_add_u64 v[76:77], v[38:39], 0, s[10:11]
	v_lshl_add_u64 v[78:79], v[36:37], 0, s[10:11]
	v_lshl_add_u64 v[80:81], v[34:35], 0, s[10:11]
	v_lshl_add_u64 v[82:83], v[32:33], 0, s[10:11]
	v_lshl_add_u64 v[84:85], v[30:31], 0, s[10:11]
	v_lshl_add_u64 v[86:87], v[28:29], 0, s[10:11]
	v_lshl_add_u64 v[88:89], v[26:27], 0, s[10:11]
	global_load_dword v106, v[74:75], off nt
	global_load_dword v107, v[76:77], off nt
	global_load_dword v108, v[78:79], off nt
	global_load_dword v109, v[80:81], off nt
	global_load_dword v110, v[82:83], off nt
	global_load_dword v111, v[84:85], off nt
	global_load_dword v112, v[86:87], off nt
	global_load_dword v113, v[88:89], off nt
	s_add_u32 s10, s10, 0x2c000
	s_addc_u32 s11, s11, 0
	v_lshl_add_u64 v[74:75], v[40:41], 0, s[10:11]
	v_lshl_add_u64 v[76:77], v[38:39], 0, s[10:11]
	v_lshl_add_u64 v[78:79], v[36:37], 0, s[10:11]
	v_lshl_add_u64 v[80:81], v[34:35], 0, s[10:11]
	v_lshl_add_u64 v[82:83], v[32:33], 0, s[10:11]
	v_lshl_add_u64 v[84:85], v[30:31], 0, s[10:11]
	v_lshl_add_u64 v[86:87], v[28:29], 0, s[10:11]
	v_lshl_add_u64 v[88:89], v[26:27], 0, s[10:11]
	global_load_dword v114, v[74:75], off nt
	global_load_dword v115, v[76:77], off nt
	global_load_dword v116, v[78:79], off nt
	global_load_dword v117, v[80:81], off nt
	global_load_dword v118, v[82:83], off nt
	global_load_dword v119, v[84:85], off nt
	global_load_dword v120, v[86:87], off nt
	global_load_dword v121, v[88:89], off nt
	s_add_u32 s10, s10, 0x2c000
	s_addc_u32 s11, s11, 0
	s_waitcnt vmcnt(24)
	v_add_u32_e32 v65, 0x400, v56
	ds_write2_b32 v56, v90, v91 offset1:66
	ds_write2_b32 v56, v92, v93 offset0:132 offset1:198
	ds_write2_b32 v65, v94, v95 offset0:8 offset1:74
	ds_write2_b32 v65, v96, v97 offset0:140 offset1:206
	v_add_u32_e32 v56, 0x840, v56
	s_waitcnt vmcnt(16)
	v_add_u32_e32 v65, 0x400, v56
	ds_write2_b32 v56, v98, v99 offset1:66
	ds_write2_b32 v56, v100, v101 offset0:132 offset1:198
	ds_write2_b32 v65, v102, v103 offset0:8 offset1:74
	ds_write2_b32 v65, v104, v105 offset0:140 offset1:206
	v_add_u32_e32 v56, 0x840, v56
	s_waitcnt vmcnt(8)
	v_add_u32_e32 v65, 0x400, v56
	ds_write2_b32 v56, v106, v107 offset1:66
	ds_write2_b32 v56, v108, v109 offset0:132 offset1:198
	ds_write2_b32 v65, v110, v111 offset0:8 offset1:74
	ds_write2_b32 v65, v112, v113 offset0:140 offset1:206
	v_add_u32_e32 v56, 0x840, v56
	s_waitcnt vmcnt(0)
	v_add_u32_e32 v65, 0x400, v56
	ds_write2_b32 v56, v114, v115 offset1:66
	ds_write2_b32 v56, v116, v117 offset0:132 offset1:198
	ds_write2_b32 v65, v118, v119 offset0:8 offset1:74
	ds_write2_b32 v65, v120, v121 offset0:140 offset1:206
	v_add_u32_e32 v56, 0x840, v56
	s_waitcnt lgkmcnt(0)
	s_lshl_b32 s11, s14, 6
	ds_read2_b32 v[30:31], v44 offset0:33 offset1:41
	ds_read2_b32 v[32:33], v44 offset1:8
	ds_read2_b32 v[34:35], v44 offset0:66 offset1:74
	ds_read2_b32 v[36:37], v44 offset0:99 offset1:107
	ds_read2_b32 v[38:39], v44 offset0:132 offset1:140
	ds_read2_b32 v[40:41], v44 offset0:165 offset1:173
	ds_read2_b32 v[56:57], v44 offset0:198 offset1:206
	ds_read2_b32 v[58:59], v44 offset0:231 offset1:239
	s_and_b32 s10, s15, 0x60
	s_and_b32 s11, s11, 0x1f00
	s_or_b32 s10, s10, s11
	s_and_b32 s11, 0xffff, s13
	s_lshl_b32 s26, s11, 1
	s_waitcnt lgkmcnt(6)
	v_cvt_pk_bf16_f32 v26, v32, v30
	v_or_b32_e32 v30, s10, v43
	v_lshl_add_u64 v[60:61], v[6:7], 0, s[26:27]
	v_lshlrev_b32_e32 v192, 11, v30
	s_waitcnt lgkmcnt(4)
	v_cvt_pk_bf16_f32 v27, v34, v36
	s_waitcnt lgkmcnt(2)
	v_cvt_pk_bf16_f32 v28, v38, v40
	s_waitcnt lgkmcnt(0)
	v_cvt_pk_bf16_f32 v29, v56, v58
	v_lshl_add_u64 v[62:63], v[60:61], 0, v[192:193]
	global_store_dwordx4 v[62:63], v[26:29], off
	v_or_b32_e32 v30, s10, v45
	v_lshlrev_b32_e32 v192, 11, v30
	v_cvt_pk_bf16_f32 v26, v33, v31
	v_cvt_pk_bf16_f32 v27, v35, v37
	v_cvt_pk_bf16_f32 v28, v39, v41
	v_cvt_pk_bf16_f32 v29, v57, v59
	ds_read2_b32 v[32:33], v44 offset0:49 offset1:57
	ds_read2_b32 v[34:35], v44 offset0:16 offset1:24
	ds_read2_b32 v[36:37], v44 offset0:82 offset1:90
	ds_read2_b32 v[38:39], v44 offset0:115 offset1:123
	ds_read2_b32 v[40:41], v44 offset0:148 offset1:156
	ds_read2_b32 v[56:57], v44 offset0:181 offset1:189
	ds_read2_b32 v[58:59], v44 offset0:214 offset1:222
	ds_read2_b32 v[62:63], v44 offset0:247 offset1:255
	v_lshl_add_u64 v[30:31], v[60:61], 0, v[192:193]
	global_store_dwordx4 v[30:31], v[26:29], off
	v_or_b32_e32 v30, s10, v46
	v_lshlrev_b32_e32 v192, 11, v30
	s_waitcnt lgkmcnt(6)
	v_cvt_pk_bf16_f32 v26, v34, v32
	s_waitcnt lgkmcnt(4)
	v_cvt_pk_bf16_f32 v27, v36, v38
	s_waitcnt lgkmcnt(2)
	v_cvt_pk_bf16_f32 v28, v40, v56
	s_waitcnt lgkmcnt(0)
	v_cvt_pk_bf16_f32 v29, v58, v62
	v_lshl_add_u64 v[30:31], v[60:61], 0, v[192:193]
	global_store_dwordx4 v[30:31], v[26:29], off
	v_or_b32_e32 v30, s10, v47
	v_lshlrev_b32_e32 v192, 11, v30
	v_cvt_pk_bf16_f32 v26, v35, v33
	v_cvt_pk_bf16_f32 v27, v37, v39
	v_cvt_pk_bf16_f32 v28, v41, v57
	v_cvt_pk_bf16_f32 v29, v59, v63
	v_lshl_add_u64 v[30:31], v[60:61], 0, v[192:193]
	global_store_dwordx4 v[30:31], v[26:29], off
	s_waitcnt lgkmcnt(0)

; #define LAS __attribute__((address_space(3)))
; __device__ __forceinline__ unsigned pk2(float lo, float hi) { f32x2 v = {lo, hi}; bf16x2_t b = __builtin_convertvector(v, bf16x2_t); return __builtin_bit_cast(unsigned, b); }
; __device__ __forceinline__ void transpose_item(const float* W, int K, int N, bf16* WT, int mode, LAS float* scr, int item, int lane) {
;     ...
; #pragma unroll 8
;     for (int i = 0; i < 32; ++i) { const int kk = 2 * i + (lane >> 5); scr[kk * 33 + (lane & 31)] = __builtin_nontemporal_load(W + (size_t)(k0 + kk) * N + n0 + (lane & 31)); }
;     asm volatile("s_waitcnt lgkmcnt(0)" ::: "memory");
;     const int c = lane & 7;
; #pragma unroll
;     for (int j = 0; j < 4; ++j) { const int n = (lane >> 3) + 8 * j; const LAS float* s = scr + (8 * c) * 33 + n;
;         u32x4 o; o.x = pk2(s[0 * 33], s[1 * 33]); o.y = pk2(s[2 * 33], s[3 * 33]); o.z = pk2(s[4 * 33], s[5 * 33]); o.w = pk2(s[6 * 33], s[7 * 33]);
;         *(u32x4*)(WT + (size_t)(r0 + n) * K + k0 + 8 * c) = o; }
;     asm volatile("s_waitcnt lgkmcnt(0)" ::: "memory");
.LBB0_689:
	v_lshl_add_u64 v[74:75], v[40:41], 0, s[10:11]
	v_lshl_add_u64 v[76:77], v[38:39], 0, s[10:11]
	v_lshl_add_u64 v[78:79], v[36:37], 0, s[10:11]
	v_lshl_add_u64 v[80:81], v[34:35], 0, s[10:11]
	v_lshl_add_u64 v[82:83], v[32:33], 0, s[10:11]
	v_lshl_add_u64 v[84:85], v[30:31], 0, s[10:11]
	v_lshl_add_u64 v[86:87], v[28:29], 0, s[10:11]
	v_lshl_add_u64 v[88:89], v[26:27], 0, s[10:11]
	global_load_dword v90, v[74:75], off nt
	global_load_dword v91, v[76:77], off nt
	global_load_dword v92, v[78:79], off nt
	global_load_dword v93, v[80:81], off nt
	global_load_dword v94, v[82:83], off nt
	global_load_dword v95, v[84:85], off nt
	global_load_dword v96, v[86:87], off nt
	global_load_dword v97, v[88:89], off nt
	s_add_u32 s10, s10, 0x10000
	s_addc_u32 s11, s11, 0
	v_lshl_add_u64 v[74:75], v[40:41], 0, s[10:11]
	v_lshl_add_u64 v[76:77], v[38:39], 0, s[10:11]
	v_lshl_add_u64 v[78:79], v[36:37], 0, s[10:11]
	v_lshl_add_u64 v[80:81], v[34:35], 0, s[10:11]
	v_lshl_add_u64 v[82:83], v[32:33], 0, s[10:11]
	v_lshl_add_u64 v[84:85], v[30:31], 0, s[10:11]
	v_lshl_add_u64 v[86:87], v[28:29], 0, s[10:11]
	v_lshl_add_u64 v[88:89], v[26:27], 0, s[10:11]
	global_load_dword v98, v[74:75], off nt
	global_load_dword v99, v[76:77], off nt
	global_load_dword v100, v[78:79], off nt
	global_load_dword v101, v[80:81], off nt
	global_load_dword v102, v[82:83], off nt
	global_load_dword v103, v[84:85], off nt
	global_load_dword v104, v[86:87], off nt
	global_load_dword v105, v[88:89], off nt
	s_add_u32 s10, s10, 0x10000
	s_addc_u32 s11, s11, 0
	v_lshl_add_u64 v[74:75], v[40:41], 0, s[10:11]
	v_lshl_add_u64 v[76:77], v[38:39], 0, s[10:11]
	v_lshl_add_u64 v[78:79], v[36:37], 0, s[10:11]
	v_lshl_add_u64 v[80:81], v[34:35], 0, s[10:11]
	v_lshl_add_u64 v[82:83], v[32:33], 0, s[10:11]
	v_lshl_add_u64 v[84:85], v[30:31], 0, s[10:11]
	v_lshl_add_u64 v[86:87], v[28:29], 0, s[10:11]
	v_lshl_add_u64 v[88:89], v[26:27], 0, s[10:11]
	global_load_dword v106, v[74:75], off nt
	global_load_dword v107, v[76:77], off nt
	global_load_dword v108, v[78:79], off nt
	global_load_dword v109, v[80:81], off nt
	global_load_dword v110, v[82:83], off nt
	global_load_dword v111, v[84:85], off nt
	global_load_dword v112, v[86:87], off nt
	global_load_dword v113, v[88:89], off nt
	s_add_u32 s10, s10, 0x10000
	s_addc_u32 s11, s11, 0
	v_lshl_add_u64 v[74:75], v[40:41], 0, s[10:11]
	v_lshl_add_u64 v[76:77], v[38:39], 0, s[10:11]
	v_lshl_add_u64 v[78:79], v[36:37], 0, s[10:11]
	v_lshl_add_u64 v[80:81], v[34:35], 0, s[10:11]
	v_lshl_add_u64 v[82:83], v[32:33], 0, s[10:11]
	v_lshl_add_u64 v[84:85], v[30:31], 0, s[10:11]
	v_lshl_add_u64 v[86:87], v[28:29], 0, s[10:11]
	v_lshl_add_u64 v[88:89], v[26:27], 0, s[10:11]
	global_load_dword v114, v[74:75], off nt
	global_load_dword v115, v[76:77], off nt
	global_load_dword v116, v[78:79], off nt
	global_load_dword v117, v[80:81], off nt
	global_load_dword v118, v[82:83], off nt
	global_load_dword v119, v[84:85], off nt
	global_load_dword v120, v[86:87], off nt
	global_load_dword v121, v[88:89], off nt
	s_add_u32 s10, s10, 0x10000
	s_addc_u32 s11, s11, 0
	s_waitcnt vmcnt(24)
	v_add_u32_e32 v65, 0x400, v56
	ds_write2_b32 v56, v90, v91 offset1:66
	ds_write2_b32 v56, v92, v93 offset0:132 offset1:198
	ds_write2_b32 v65, v94, v95 offset0:8 offset1:74
	ds_write2_b32 v65, v96, v97 offset0:140 offset1:206
	v_add_u32_e32 v56, 0x840, v56
	s_waitcnt vmcnt(16)
	v_add_u32_e32 v65, 0x400, v56
	ds_write2_b32 v56, v98, v99 offset1:66
	ds_write2_b32 v56, v100, v101 offset0:132 offset1:198
	ds_write2_b32 v65, v102, v103 offset0:8 offset1:74
	ds_write2_b32 v65, v104, v105 offset0:140 offset1:206
	v_add_u32_e32 v56, 0x840, v56
	s_waitcnt vmcnt(8)
	v_add_u32_e32 v65, 0x400, v56
	ds_write2_b32 v56, v106, v107 offset1:66
	ds_write2_b32 v56, v108, v109 offset0:132 offset1:198
	ds_write2_b32 v65, v110, v111 offset0:8 offset1:74
	ds_write2_b32 v65, v112, v113 offset0:140 offset1:206
	v_add_u32_e32 v56, 0x840, v56
	s_waitcnt vmcnt(0)
	v_add_u32_e32 v65, 0x400, v56
	ds_write2_b32 v56, v114, v115 offset1:66
	ds_write2_b32 v56, v116, v117 offset0:132 offset1:198
	ds_write2_b32 v65, v118, v119 offset0:8 offset1:74
	ds_write2_b32 v65, v120, v121 offset0:140 offset1:206
	v_add_u32_e32 v56, 0x840, v56
	s_waitcnt lgkmcnt(0)
	s_lshl_b32 s10, s19, 1
	ds_read2_b32 v[30:31], v44 offset0:33 offset1:41
	ds_read2_b32 v[32:33], v44 offset1:8
	ds_read2_b32 v[34:35], v44 offset0:66 offset1:74
	ds_read2_b32 v[36:37], v44 offset0:99 offset1:107
	ds_read2_b32 v[38:39], v44 offset0:132 offset1:140
	ds_read2_b32 v[40:41], v44 offset0:165 offset1:173
	ds_read2_b32 v[56:57], v44 offset0:198 offset1:206
	ds_read2_b32 v[58:59], v44 offset0:231 offset1:239
	s_add_i32 s10, s10, 0x1da00
	s_lshl_b32 s11, s19, 5
	s_and_b32 s10, s10, 0x1ffc0
	s_and_b32 s11, s11, 0x3e0
	s_lshl_b32 s26, s10, 1
	s_waitcnt lgkmcnt(6)
	v_cvt_pk_bf16_f32 v26, v32, v30
	v_or_b32_e32 v30, s11, v43
	v_lshl_add_u64 v[60:61], v[8:9], 0, s[26:27]
	v_lshlrev_b32_e32 v192, 11, v30
	s_waitcnt lgkmcnt(4)
	v_cvt_pk_bf16_f32 v27, v34, v36
	s_waitcnt lgkmcnt(2)
	v_cvt_pk_bf16_f32 v28, v38, v40
	s_waitcnt lgkmcnt(0)
	v_cvt_pk_bf16_f32 v29, v56, v58
	v_lshl_add_u64 v[62:63], v[60:61], 0, v[192:193]
	global_store_dwordx4 v[62:63], v[26:29], off
	v_or_b32_e32 v30, s11, v45
	v_lshlrev_b32_e32 v192, 11, v30
	v_cvt_pk_bf16_f32 v26, v33, v31
	v_cvt_pk_bf16_f32 v27, v35, v37
	v_cvt_pk_bf16_f32 v28, v39, v41
	v_cvt_pk_bf16_f32 v29, v57, v59
	ds_read2_b32 v[32:33], v44 offset0:49 offset1:57
	ds_read2_b32 v[34:35], v44 offset0:16 offset1:24
	ds_read2_b32 v[36:37], v44 offset0:82 offset1:90
	ds_read2_b32 v[38:39], v44 offset0:115 offset1:123
	ds_read2_b32 v[40:41], v44 offset0:148 offset1:156
	ds_read2_b32 v[56:57], v44 offset0:181 offset1:189
	ds_read2_b32 v[58:59], v44 offset0:214 offset1:222
	ds_read2_b32 v[62:63], v44 offset0:247 offset1:255
	v_lshl_add_u64 v[30:31], v[60:61], 0, v[192:193]
	global_store_dwordx4 v[30:31], v[26:29], off
	v_or_b32_e32 v30, s11, v46
	v_lshlrev_b32_e32 v192, 11, v30
	s_waitcnt lgkmcnt(6)
	v_cvt_pk_bf16_f32 v26, v34, v32
	s_waitcnt lgkmcnt(4)
	v_cvt_pk_bf16_f32 v27, v36, v38
	s_waitcnt lgkmcnt(2)
	v_cvt_pk_bf16_f32 v28, v40, v56
	s_waitcnt lgkmcnt(0)
	v_cvt_pk_bf16_f32 v29, v58, v62
	v_lshl_add_u64 v[30:31], v[60:61], 0, v[192:193]
	global_store_dwordx4 v[30:31], v[26:29], off
	v_or_b32_e32 v30, s11, v47
	v_lshlrev_b32_e32 v192, 11, v30
	v_cvt_pk_bf16_f32 v26, v35, v33
	v_cvt_pk_bf16_f32 v27, v37, v39
	v_cvt_pk_bf16_f32 v28, v41, v57
	v_cvt_pk_bf16_f32 v29, v59, v63
	v_lshl_add_u64 v[30:31], v[60:61], 0, v[192:193]
	global_store_dwordx4 v[30:31], v[26:29], off
	s_waitcnt lgkmcnt(0)

; #define LAS __attribute__((address_space(3)))
; __device__ __forceinline__ unsigned pk2(float lo, float hi) { f32x2 v = {lo, hi}; bf16x2_t b = __builtin_convertvector(v, bf16x2_t); return __builtin_bit_cast(unsigned, b); }
; __device__ __forceinline__ void transpose_item(const float* W, int K, int N, bf16* WT, int mode, LAS float* scr, int item, int lane) {
;     ...
; #pragma unroll 8
;     for (int i = 0; i < 32; ++i) { const int kk = 2 * i + (lane >> 5); scr[kk * 33 + (lane & 31)] = __builtin_nontemporal_load(W + (size_t)(k0 + kk) * N + n0 + (lane & 31)); }
;     asm volatile("s_waitcnt lgkmcnt(0)" ::: "memory");
;     const int c = lane & 7;
; #pragma unroll
;     for (int j = 0; j < 4; ++j) { const int n = (lane >> 3) + 8 * j; const LAS float* s = scr + (8 * c) * 33 + n;
;         u32x4 o; o.x = pk2(s[0 * 33], s[1 * 33]); o.y = pk2(s[2 * 33], s[3 * 33]); o.z = pk2(s[4 * 33], s[5 * 33]); o.w = pk2(s[6 * 33], s[7 * 33]);
;         *(u32x4*)(WT + (size_t)(r0 + n) * K + k0 + 8 * c) = o; }
;     asm volatile("s_waitcnt lgkmcnt(0)" ::: "memory");
.LBB0_694:
	v_lshl_add_u64 v[74:75], v[40:41], 0, s[10:11]
	v_lshl_add_u64 v[76:77], v[38:39], 0, s[10:11]
	v_lshl_add_u64 v[78:79], v[36:37], 0, s[10:11]
	v_lshl_add_u64 v[80:81], v[34:35], 0, s[10:11]
	v_lshl_add_u64 v[82:83], v[32:33], 0, s[10:11]
	v_lshl_add_u64 v[84:85], v[30:31], 0, s[10:11]
	v_lshl_add_u64 v[86:87], v[28:29], 0, s[10:11]
	v_lshl_add_u64 v[88:89], v[26:27], 0, s[10:11]
	global_load_dword v90, v[74:75], off nt
	global_load_dword v91, v[76:77], off nt
	global_load_dword v92, v[78:79], off nt
	global_load_dword v93, v[80:81], off nt
	global_load_dword v94, v[82:83], off nt
	global_load_dword v95, v[84:85], off nt
	global_load_dword v96, v[86:87], off nt
	global_load_dword v97, v[88:89], off nt
	s_add_u32 s10, s10, 0x10000
	s_addc_u32 s11, s11, 0
	v_lshl_add_u64 v[74:75], v[40:41], 0, s[10:11]
	v_lshl_add_u64 v[76:77], v[38:39], 0, s[10:11]
	v_lshl_add_u64 v[78:79], v[36:37], 0, s[10:11]
	v_lshl_add_u64 v[80:81], v[34:35], 0, s[10:11]
	v_lshl_add_u64 v[82:83], v[32:33], 0, s[10:11]
	v_lshl_add_u64 v[84:85], v[30:31], 0, s[10:11]
	v_lshl_add_u64 v[86:87], v[28:29], 0, s[10:11]
	v_lshl_add_u64 v[88:89], v[26:27], 0, s[10:11]
	global_load_dword v98, v[74:75], off nt
	global_load_dword v99, v[76:77], off nt
	global_load_dword v100, v[78:79], off nt
	global_load_dword v101, v[80:81], off nt
	global_load_dword v102, v[82:83], off nt
	global_load_dword v103, v[84:85], off nt
	global_load_dword v104, v[86:87], off nt
	global_load_dword v105, v[88:89], off nt
	s_add_u32 s10, s10, 0x10000
	s_addc_u32 s11, s11, 0
	v_lshl_add_u64 v[74:75], v[40:41], 0, s[10:11]
	v_lshl_add_u64 v[76:77], v[38:39], 0, s[10:11]
	v_lshl_add_u64 v[78:79], v[36:37], 0, s[10:11]
	v_lshl_add_u64 v[80:81], v[34:35], 0, s[10:11]
	v_lshl_add_u64 v[82:83], v[32:33], 0, s[10:11]
	v_lshl_add_u64 v[84:85], v[30:31], 0, s[10:11]
	v_lshl_add_u64 v[86:87], v[28:29], 0, s[10:11]
	v_lshl_add_u64 v[88:89], v[26:27], 0, s[10:11]
	global_load_dword v106, v[74:75], off nt
	global_load_dword v107, v[76:77], off nt
	global_load_dword v108, v[78:79], off nt
	global_load_dword v109, v[80:81], off nt
	global_load_dword v110, v[82:83], off nt
	global_load_dword v111, v[84:85], off nt
	global_load_dword v112, v[86:87], off nt
	global_load_dword v113, v[88:89], off nt
	s_add_u32 s10, s10, 0x10000
	s_addc_u32 s11, s11, 0
	v_lshl_add_u64 v[74:75], v[40:41], 0, s[10:11]
	v_lshl_add_u64 v[76:77], v[38:39], 0, s[10:11]
	v_lshl_add_u64 v[78:79], v[36:37], 0, s[10:11]
	v_lshl_add_u64 v[80:81], v[34:35], 0, s[10:11]
	v_lshl_add_u64 v[82:83], v[32:33], 0, s[10:11]
	v_lshl_add_u64 v[84:85], v[30:31], 0, s[10:11]
	v_lshl_add_u64 v[86:87], v[28:29], 0, s[10:11]
	v_lshl_add_u64 v[88:89], v[26:27], 0, s[10:11]
	global_load_dword v114, v[74:75], off nt
	global_load_dword v115, v[76:77], off nt
	global_load_dword v116, v[78:79], off nt
	global_load_dword v117, v[80:81], off nt
	global_load_dword v118, v[82:83], off nt
	global_load_dword v119, v[84:85], off nt
	global_load_dword v120, v[86:87], off nt
	global_load_dword v121, v[88:89], off nt
	s_add_u32 s10, s10, 0x10000
	s_addc_u32 s11, s11, 0
	s_waitcnt vmcnt(24)
	v_add_u32_e32 v65, 0x400, v56
	ds_write2_b32 v56, v90, v91 offset1:66
	ds_write2_b32 v56, v92, v93 offset0:132 offset1:198
	ds_write2_b32 v65, v94, v95 offset0:8 offset1:74
	ds_write2_b32 v65, v96, v97 offset0:140 offset1:206
	v_add_u32_e32 v56, 0x840, v56
	s_waitcnt vmcnt(16)
	v_add_u32_e32 v65, 0x400, v56
	ds_write2_b32 v56, v98, v99 offset1:66
	ds_write2_b32 v56, v100, v101 offset0:132 offset1:198
	ds_write2_b32 v65, v102, v103 offset0:8 offset1:74
	ds_write2_b32 v65, v104, v105 offset0:140 offset1:206
	v_add_u32_e32 v56, 0x840, v56
	s_waitcnt vmcnt(8)
	v_add_u32_e32 v65, 0x400, v56
	ds_write2_b32 v56, v106, v107 offset1:66
	ds_write2_b32 v56, v108, v109 offset0:132 offset1:198
	ds_write2_b32 v65, v110, v111 offset0:8 offset1:74
	ds_write2_b32 v65, v112, v113 offset0:140 offset1:206
	v_add_u32_e32 v56, 0x840, v56
	s_waitcnt vmcnt(0)
	v_add_u32_e32 v65, 0x400, v56
	ds_write2_b32 v56, v114, v115 offset1:66
	ds_write2_b32 v56, v116, v117 offset0:132 offset1:198
	ds_write2_b32 v65, v118, v119 offset0:8 offset1:74
	ds_write2_b32 v65, v120, v121 offset0:140 offset1:206
	v_add_u32_e32 v56, 0x840, v56
	s_waitcnt lgkmcnt(0)
	ds_read2_b32 v[30:31], v44 offset0:33 offset1:41
	ds_read2_b32 v[32:33], v44 offset1:8
	ds_read2_b32 v[34:35], v44 offset0:66 offset1:74
	ds_read2_b32 v[36:37], v44 offset0:99 offset1:107
	ds_read2_b32 v[38:39], v44 offset0:132 offset1:140
	ds_read2_b32 v[40:41], v44 offset0:165 offset1:173
	ds_read2_b32 v[56:57], v44 offset0:198 offset1:206
	ds_read2_b32 v[58:59], v44 offset0:231 offset1:239
	s_lshl_b32 s10, s19, 5
	s_and_b32 s10, s10, 0x3e0
	s_lshl_b32 s11, s19, 2
	s_and_b32 s26, s11, 0x380
	s_waitcnt lgkmcnt(6)
	v_cvt_pk_bf16_f32 v26, v32, v30
	v_or_b32_e32 v30, s10, v43
	v_lshl_add_u64 v[60:61], v[10:11], 0, s[26:27]
	v_lshlrev_b32_e32 v192, 10, v30
	s_waitcnt lgkmcnt(4)
	v_cvt_pk_bf16_f32 v27, v34, v36
	s_waitcnt lgkmcnt(2)
	v_cvt_pk_bf16_f32 v28, v38, v40
	s_waitcnt lgkmcnt(0)
	v_cvt_pk_bf16_f32 v29, v56, v58
	v_lshl_add_u64 v[62:63], v[60:61], 0, v[192:193]
	global_store_dwordx4 v[62:63], v[26:29], off
	v_or_b32_e32 v30, s10, v45
	v_lshlrev_b32_e32 v192, 10, v30
	v_cvt_pk_bf16_f32 v26, v33, v31
	v_cvt_pk_bf16_f32 v27, v35, v37
	v_cvt_pk_bf16_f32 v28, v39, v41
	v_cvt_pk_bf16_f32 v29, v57, v59
	ds_read2_b32 v[32:33], v44 offset0:49 offset1:57
	ds_read2_b32 v[34:35], v44 offset0:16 offset1:24
	ds_read2_b32 v[36:37], v44 offset0:82 offset1:90
	ds_read2_b32 v[38:39], v44 offset0:115 offset1:123
	ds_read2_b32 v[40:41], v44 offset0:148 offset1:156
	ds_read2_b32 v[56:57], v44 offset0:181 offset1:189
	ds_read2_b32 v[58:59], v44 offset0:214 offset1:222
	ds_read2_b32 v[62:63], v44 offset0:247 offset1:255
	v_lshl_add_u64 v[30:31], v[60:61], 0, v[192:193]
	global_store_dwordx4 v[30:31], v[26:29], off
	v_or_b32_e32 v30, s10, v46
	v_lshlrev_b32_e32 v192, 10, v30
	s_waitcnt lgkmcnt(6)
	v_cvt_pk_bf16_f32 v26, v34, v32
	s_waitcnt lgkmcnt(4)
	v_cvt_pk_bf16_f32 v27, v36, v38
	s_waitcnt lgkmcnt(2)
	v_cvt_pk_bf16_f32 v28, v40, v56
	s_waitcnt lgkmcnt(0)
	v_cvt_pk_bf16_f32 v29, v58, v62
	v_lshl_add_u64 v[30:31], v[60:61], 0, v[192:193]
	global_store_dwordx4 v[30:31], v[26:29], off
	v_or_b32_e32 v30, s10, v47
	v_lshlrev_b32_e32 v192, 10, v30
	v_cvt_pk_bf16_f32 v26, v35, v33
	v_cvt_pk_bf16_f32 v27, v37, v39
	v_cvt_pk_bf16_f32 v28, v41, v57
	v_cvt_pk_bf16_f32 v29, v59, v63
	v_lshl_add_u64 v[30:31], v[60:61], 0, v[192:193]
	global_store_dwordx4 v[30:31], v[26:29], off
	s_waitcnt lgkmcnt(0)

; #define LAS __attribute__((address_space(3)))
; __device__ __forceinline__ unsigned pk2(float lo, float hi) { f32x2 v = {lo, hi}; bf16x2_t b = __builtin_convertvector(v, bf16x2_t); return __builtin_bit_cast(unsigned, b); }
; __device__ __forceinline__ void transpose_item(const float* W, int K, int N, bf16* WT, int mode, LAS float* scr, int item, int lane) {
;     ...
; #pragma unroll 8
;     for (int i = 0; i < 32; ++i) { const int kk = 2 * i + (lane >> 5); scr[kk * 33 + (lane & 31)] = __builtin_nontemporal_load(W + (size_t)(k0 + kk) * N + n0 + (lane & 31)); }
;     asm volatile("s_waitcnt lgkmcnt(0)" ::: "memory");
;     const int c = lane & 7;
; #pragma unroll
;     for (int j = 0; j < 4; ++j) { const int n = (lane >> 3) + 8 * j; const LAS float* s = scr + (8 * c) * 33 + n;
;         u32x4 o; o.x = pk2(s[0 * 33], s[1 * 33]); o.y = pk2(s[2 * 33], s[3 * 33]); o.z = pk2(s[4 * 33], s[5 * 33]); o.w = pk2(s[6 * 33], s[7 * 33]);
;         *(u32x4*)(WT + (size_t)(r0 + n) * K + k0 + 8 * c) = o; }
;     asm volatile("s_waitcnt lgkmcnt(0)" ::: "memory");
.LBB0_699:
	v_lshl_add_u64 v[74:75], v[40:41], 0, s[10:11]
	v_lshl_add_u64 v[76:77], v[38:39], 0, s[10:11]
	v_lshl_add_u64 v[78:79], v[36:37], 0, s[10:11]
	v_lshl_add_u64 v[80:81], v[34:35], 0, s[10:11]
	v_lshl_add_u64 v[82:83], v[32:33], 0, s[10:11]
	v_lshl_add_u64 v[84:85], v[30:31], 0, s[10:11]
	v_lshl_add_u64 v[86:87], v[28:29], 0, s[10:11]
	v_lshl_add_u64 v[88:89], v[26:27], 0, s[10:11]
	global_load_dword v90, v[74:75], off nt
	global_load_dword v91, v[76:77], off nt
	global_load_dword v92, v[78:79], off nt
	global_load_dword v93, v[80:81], off nt
	global_load_dword v94, v[82:83], off nt
	global_load_dword v95, v[84:85], off nt
	global_load_dword v96, v[86:87], off nt
	global_load_dword v97, v[88:89], off nt
	s_add_u32 s10, s10, 0x10000
	s_addc_u32 s11, s11, 0
	v_lshl_add_u64 v[74:75], v[40:41], 0, s[10:11]
	v_lshl_add_u64 v[76:77], v[38:39], 0, s[10:11]
	v_lshl_add_u64 v[78:79], v[36:37], 0, s[10:11]
	v_lshl_add_u64 v[80:81], v[34:35], 0, s[10:11]
	v_lshl_add_u64 v[82:83], v[32:33], 0, s[10:11]
	v_lshl_add_u64 v[84:85], v[30:31], 0, s[10:11]
	v_lshl_add_u64 v[86:87], v[28:29], 0, s[10:11]
	v_lshl_add_u64 v[88:89], v[26:27], 0, s[10:11]
	global_load_dword v98, v[74:75], off nt
	global_load_dword v99, v[76:77], off nt
	global_load_dword v100, v[78:79], off nt
	global_load_dword v101, v[80:81], off nt
	global_load_dword v102, v[82:83], off nt
	global_load_dword v103, v[84:85], off nt
	global_load_dword v104, v[86:87], off nt
	global_load_dword v105, v[88:89], off nt
	s_add_u32 s10, s10, 0x10000
	s_addc_u32 s11, s11, 0
	v_lshl_add_u64 v[74:75], v[40:41], 0, s[10:11]
	v_lshl_add_u64 v[76:77], v[38:39], 0, s[10:11]
	v_lshl_add_u64 v[78:79], v[36:37], 0, s[10:11]
	v_lshl_add_u64 v[80:81], v[34:35], 0, s[10:11]
	v_lshl_add_u64 v[82:83], v[32:33], 0, s[10:11]
	v_lshl_add_u64 v[84:85], v[30:31], 0, s[10:11]
	v_lshl_add_u64 v[86:87], v[28:29], 0, s[10:11]
	v_lshl_add_u64 v[88:89], v[26:27], 0, s[10:11]
	global_load_dword v106, v[74:75], off nt
	global_load_dword v107, v[76:77], off nt
	global_load_dword v108, v[78:79], off nt
	global_load_dword v109, v[80:81], off nt
	global_load_dword v110, v[82:83], off nt
	global_load_dword v111, v[84:85], off nt
	global_load_dword v112, v[86:87], off nt
	global_load_dword v113, v[88:89], off nt
	s_add_u32 s10, s10, 0x10000
	s_addc_u32 s11, s11, 0
	v_lshl_add_u64 v[74:75], v[40:41], 0, s[10:11]
	v_lshl_add_u64 v[76:77], v[38:39], 0, s[10:11]
	v_lshl_add_u64 v[78:79], v[36:37], 0, s[10:11]
	v_lshl_add_u64 v[80:81], v[34:35], 0, s[10:11]
	v_lshl_add_u64 v[82:83], v[32:33], 0, s[10:11]
	v_lshl_add_u64 v[84:85], v[30:31], 0, s[10:11]
	v_lshl_add_u64 v[86:87], v[28:29], 0, s[10:11]
	v_lshl_add_u64 v[88:89], v[26:27], 0, s[10:11]
	global_load_dword v114, v[74:75], off nt
	global_load_dword v115, v[76:77], off nt
	global_load_dword v116, v[78:79], off nt
	global_load_dword v117, v[80:81], off nt
	global_load_dword v118, v[82:83], off nt
	global_load_dword v119, v[84:85], off nt
	global_load_dword v120, v[86:87], off nt
	global_load_dword v121, v[88:89], off nt
	s_add_u32 s10, s10, 0x10000
	s_addc_u32 s11, s11, 0
	s_waitcnt vmcnt(24)
	v_add_u32_e32 v65, 0x400, v56
	ds_write2_b32 v56, v90, v91 offset1:66
	ds_write2_b32 v56, v92, v93 offset0:132 offset1:198
	ds_write2_b32 v65, v94, v95 offset0:8 offset1:74
	ds_write2_b32 v65, v96, v97 offset0:140 offset1:206
	v_add_u32_e32 v56, 0x840, v56
	s_waitcnt vmcnt(16)
	v_add_u32_e32 v65, 0x400, v56
	ds_write2_b32 v56, v98, v99 offset1:66
	ds_write2_b32 v56, v100, v101 offset0:132 offset1:198
	ds_write2_b32 v65, v102, v103 offset0:8 offset1:74
	ds_write2_b32 v65, v104, v105 offset0:140 offset1:206
	v_add_u32_e32 v56, 0x840, v56
	s_waitcnt vmcnt(8)
	v_add_u32_e32 v65, 0x400, v56
	ds_write2_b32 v56, v106, v107 offset1:66
	ds_write2_b32 v56, v108, v109 offset0:132 offset1:198
	ds_write2_b32 v65, v110, v111 offset0:8 offset1:74
	ds_write2_b32 v65, v112, v113 offset0:140 offset1:206
	v_add_u32_e32 v56, 0x840, v56
	s_waitcnt vmcnt(0)
	v_add_u32_e32 v65, 0x400, v56
	ds_write2_b32 v56, v114, v115 offset1:66
	ds_write2_b32 v56, v116, v117 offset0:132 offset1:198
	ds_write2_b32 v65, v118, v119 offset0:8 offset1:74
	ds_write2_b32 v65, v120, v121 offset0:140 offset1:206
	v_add_u32_e32 v56, 0x840, v56
	s_waitcnt lgkmcnt(0)
	s_lshl_b32 s10, s19, 1
	ds_read2_b32 v[30:31], v44 offset0:33 offset1:41
	ds_read2_b32 v[32:33], v44 offset1:8
	ds_read2_b32 v[34:35], v44 offset0:66 offset1:74
	ds_read2_b32 v[36:37], v44 offset0:99 offset1:107
	ds_read2_b32 v[38:39], v44 offset0:132 offset1:140
	ds_read2_b32 v[40:41], v44 offset0:165 offset1:173
	ds_read2_b32 v[56:57], v44 offset0:198 offset1:206
	ds_read2_b32 v[58:59], v44 offset0:231 offset1:239
	s_add_i32 s10, s10, 0x1e000
	s_lshl_b32 s11, s19, 5
	s_and_b32 s10, s10, 0x1ffc0
	s_and_b32 s11, s11, 0x3e0
	s_lshl_b32 s26, s10, 1
	s_waitcnt lgkmcnt(6)
	v_cvt_pk_bf16_f32 v26, v32, v30
	v_or_b32_e32 v30, s11, v43
	v_lshl_add_u64 v[60:61], v[12:13], 0, s[26:27]
	v_lshlrev_b32_e32 v192, 11, v30
	s_waitcnt lgkmcnt(4)
	v_cvt_pk_bf16_f32 v27, v34, v36
	s_waitcnt lgkmcnt(2)
	v_cvt_pk_bf16_f32 v28, v38, v40
	s_waitcnt lgkmcnt(0)
	v_cvt_pk_bf16_f32 v29, v56, v58
	v_lshl_add_u64 v[62:63], v[60:61], 0, v[192:193]
	global_store_dwordx4 v[62:63], v[26:29], off
	v_or_b32_e32 v30, s11, v45
	v_lshlrev_b32_e32 v192, 11, v30
	v_cvt_pk_bf16_f32 v26, v33, v31
	v_cvt_pk_bf16_f32 v27, v35, v37
	v_cvt_pk_bf16_f32 v28, v39, v41
	v_cvt_pk_bf16_f32 v29, v57, v59
	ds_read2_b32 v[32:33], v44 offset0:49 offset1:57
	ds_read2_b32 v[34:35], v44 offset0:16 offset1:24
	ds_read2_b32 v[36:37], v44 offset0:82 offset1:90
	ds_read2_b32 v[38:39], v44 offset0:115 offset1:123
	ds_read2_b32 v[40:41], v44 offset0:148 offset1:156
	ds_read2_b32 v[56:57], v44 offset0:181 offset1:189
	ds_read2_b32 v[58:59], v44 offset0:214 offset1:222
	ds_read2_b32 v[62:63], v44 offset0:247 offset1:255
	v_lshl_add_u64 v[30:31], v[60:61], 0, v[192:193]
	global_store_dwordx4 v[30:31], v[26:29], off
	v_or_b32_e32 v30, s11, v46
	v_lshlrev_b32_e32 v192, 11, v30
	s_waitcnt lgkmcnt(6)
	v_cvt_pk_bf16_f32 v26, v34, v32
	s_waitcnt lgkmcnt(4)
	v_cvt_pk_bf16_f32 v27, v36, v38
	s_waitcnt lgkmcnt(2)
	v_cvt_pk_bf16_f32 v28, v40, v56
	s_waitcnt lgkmcnt(0)
	v_cvt_pk_bf16_f32 v29, v58, v62
	v_lshl_add_u64 v[30:31], v[60:61], 0, v[192:193]
	global_store_dwordx4 v[30:31], v[26:29], off
	v_or_b32_e32 v30, s11, v47
	v_lshlrev_b32_e32 v192, 11, v30
	v_cvt_pk_bf16_f32 v26, v35, v33
	v_cvt_pk_bf16_f32 v27, v37, v39
	v_cvt_pk_bf16_f32 v28, v41, v57
	v_cvt_pk_bf16_f32 v29, v59, v63
	v_lshl_add_u64 v[30:31], v[60:61], 0, v[192:193]
	global_store_dwordx4 v[30:31], v[26:29], off
	s_waitcnt lgkmcnt(0)

; #define LAS __attribute__((address_space(3)))
; __device__ __forceinline__ unsigned pk2(float lo, float hi) { f32x2 v = {lo, hi}; bf16x2_t b = __builtin_convertvector(v, bf16x2_t); return __builtin_bit_cast(unsigned, b); }
; __device__ __forceinline__ void transpose_item(const float* W, int K, int N, bf16* WT, int mode, LAS float* scr, int item, int lane) {
;     ...
; #pragma unroll 8
;     for (int i = 0; i < 32; ++i) { const int kk = 2 * i + (lane >> 5); scr[kk * 33 + (lane & 31)] = __builtin_nontemporal_load(W + (size_t)(k0 + kk) * N + n0 + (lane & 31)); }
;     asm volatile("s_waitcnt lgkmcnt(0)" ::: "memory");
;     const int c = lane & 7;
; #pragma unroll
;     for (int j = 0; j < 4; ++j) { const int n = (lane >> 3) + 8 * j; const LAS float* s = scr + (8 * c) * 33 + n;
;         u32x4 o; o.x = pk2(s[0 * 33], s[1 * 33]); o.y = pk2(s[2 * 33], s[3 * 33]); o.z = pk2(s[4 * 33], s[5 * 33]); o.w = pk2(s[6 * 33], s[7 * 33]);
;         *(u32x4*)(WT + (size_t)(r0 + n) * K + k0 + 8 * c) = o; }
;     asm volatile("s_waitcnt lgkmcnt(0)" ::: "memory");
.LBB0_704:
	v_lshl_add_u64 v[74:75], v[40:41], 0, s[14:15]
	v_lshl_add_u64 v[76:77], v[38:39], 0, s[14:15]
	v_lshl_add_u64 v[78:79], v[36:37], 0, s[14:15]
	v_lshl_add_u64 v[80:81], v[34:35], 0, s[14:15]
	v_lshl_add_u64 v[82:83], v[32:33], 0, s[14:15]
	v_lshl_add_u64 v[84:85], v[30:31], 0, s[14:15]
	v_lshl_add_u64 v[86:87], v[28:29], 0, s[14:15]
	v_lshl_add_u64 v[88:89], v[26:27], 0, s[14:15]
	global_load_dword v90, v[74:75], off nt
	global_load_dword v91, v[76:77], off nt
	global_load_dword v92, v[78:79], off nt
	global_load_dword v93, v[80:81], off nt
	global_load_dword v94, v[82:83], off nt
	global_load_dword v95, v[84:85], off nt
	global_load_dword v96, v[86:87], off nt
	global_load_dword v97, v[88:89], off nt
	s_add_u32 s14, s14, 0x80000
	s_addc_u32 s15, s15, 0
	v_lshl_add_u64 v[74:75], v[40:41], 0, s[14:15]
	v_lshl_add_u64 v[76:77], v[38:39], 0, s[14:15]
	v_lshl_add_u64 v[78:79], v[36:37], 0, s[14:15]
	v_lshl_add_u64 v[80:81], v[34:35], 0, s[14:15]
	v_lshl_add_u64 v[82:83], v[32:33], 0, s[14:15]
	v_lshl_add_u64 v[84:85], v[30:31], 0, s[14:15]
	v_lshl_add_u64 v[86:87], v[28:29], 0, s[14:15]
	v_lshl_add_u64 v[88:89], v[26:27], 0, s[14:15]
	global_load_dword v98, v[74:75], off nt
	global_load_dword v99, v[76:77], off nt
	global_load_dword v100, v[78:79], off nt
	global_load_dword v101, v[80:81], off nt
	global_load_dword v102, v[82:83], off nt
	global_load_dword v103, v[84:85], off nt
	global_load_dword v104, v[86:87], off nt
	global_load_dword v105, v[88:89], off nt
	s_add_u32 s14, s14, 0x80000
	s_addc_u32 s15, s15, 0
	v_lshl_add_u64 v[74:75], v[40:41], 0, s[14:15]
	v_lshl_add_u64 v[76:77], v[38:39], 0, s[14:15]
	v_lshl_add_u64 v[78:79], v[36:37], 0, s[14:15]
	v_lshl_add_u64 v[80:81], v[34:35], 0, s[14:15]
	v_lshl_add_u64 v[82:83], v[32:33], 0, s[14:15]
	v_lshl_add_u64 v[84:85], v[30:31], 0, s[14:15]
	v_lshl_add_u64 v[86:87], v[28:29], 0, s[14:15]
	v_lshl_add_u64 v[88:89], v[26:27], 0, s[14:15]
	global_load_dword v106, v[74:75], off nt
	global_load_dword v107, v[76:77], off nt
	global_load_dword v108, v[78:79], off nt
	global_load_dword v109, v[80:81], off nt
	global_load_dword v110, v[82:83], off nt
	global_load_dword v111, v[84:85], off nt
	global_load_dword v112, v[86:87], off nt
	global_load_dword v113, v[88:89], off nt
	s_add_u32 s14, s14, 0x80000
	s_addc_u32 s15, s15, 0
	v_lshl_add_u64 v[74:75], v[40:41], 0, s[14:15]
	v_lshl_add_u64 v[76:77], v[38:39], 0, s[14:15]
	v_lshl_add_u64 v[78:79], v[36:37], 0, s[14:15]
	v_lshl_add_u64 v[80:81], v[34:35], 0, s[14:15]
	v_lshl_add_u64 v[82:83], v[32:33], 0, s[14:15]
	v_lshl_add_u64 v[84:85], v[30:31], 0, s[14:15]
	v_lshl_add_u64 v[86:87], v[28:29], 0, s[14:15]
	v_lshl_add_u64 v[88:89], v[26:27], 0, s[14:15]
	global_load_dword v114, v[74:75], off nt
	global_load_dword v115, v[76:77], off nt
	global_load_dword v116, v[78:79], off nt
	global_load_dword v117, v[80:81], off nt
	global_load_dword v118, v[82:83], off nt
	global_load_dword v119, v[84:85], off nt
	global_load_dword v120, v[86:87], off nt
	global_load_dword v121, v[88:89], off nt
	s_add_u32 s14, s14, 0x80000
	s_addc_u32 s15, s15, 0
	s_waitcnt vmcnt(24)
	v_add_u32_e32 v65, 0x400, v56
	ds_write2_b32 v56, v90, v91 offset1:66
	ds_write2_b32 v56, v92, v93 offset0:132 offset1:198
	ds_write2_b32 v65, v94, v95 offset0:8 offset1:74
	ds_write2_b32 v65, v96, v97 offset0:140 offset1:206
	v_add_u32_e32 v56, 0x840, v56
	s_waitcnt vmcnt(16)
	v_add_u32_e32 v65, 0x400, v56
	ds_write2_b32 v56, v98, v99 offset1:66
	ds_write2_b32 v56, v100, v101 offset0:132 offset1:198
	ds_write2_b32 v65, v102, v103 offset0:8 offset1:74
	ds_write2_b32 v65, v104, v105 offset0:140 offset1:206
	v_add_u32_e32 v56, 0x840, v56
	s_waitcnt vmcnt(8)
	v_add_u32_e32 v65, 0x400, v56
	ds_write2_b32 v56, v106, v107 offset1:66
	ds_write2_b32 v56, v108, v109 offset0:132 offset1:198
	ds_write2_b32 v65, v110, v111 offset0:8 offset1:74
	ds_write2_b32 v65, v112, v113 offset0:140 offset1:206
	v_add_u32_e32 v56, 0x840, v56
	s_waitcnt vmcnt(0)
	v_add_u32_e32 v65, 0x400, v56
	ds_write2_b32 v56, v114, v115 offset1:66
	ds_write2_b32 v56, v116, v117 offset0:132 offset1:198
	ds_write2_b32 v65, v118, v119 offset0:8 offset1:74
	ds_write2_b32 v65, v120, v121 offset0:140 offset1:206
	v_add_u32_e32 v56, 0x840, v56
	s_waitcnt lgkmcnt(0)
	ds_read2_b32 v[30:31], v44 offset0:33 offset1:41
	ds_read2_b32 v[32:33], v44 offset1:8
	ds_read2_b32 v[34:35], v44 offset0:66 offset1:74
	ds_read2_b32 v[36:37], v44 offset0:99 offset1:107
	ds_read2_b32 v[38:39], v44 offset0:132 offset1:140
	ds_read2_b32 v[40:41], v44 offset0:165 offset1:173
	ds_read2_b32 v[56:57], v44 offset0:198 offset1:206
	ds_read2_b32 v[58:59], v44 offset0:231 offset1:239
	v_or_b32_e32 v62, s10, v43
	s_ashr_i32 s13, s12, 31
	v_ashrrev_i32_e32 v63, 31, v62
	v_lshl_add_u64 v[60:61], s[12:13], 1, v[14:15]
	v_lshlrev_b64 v[62:63], 11, v[62:63]
	s_waitcnt lgkmcnt(6)
	v_cvt_pk_bf16_f32 v26, v32, v30
	s_waitcnt lgkmcnt(4)
	v_cvt_pk_bf16_f32 v27, v34, v36
	s_waitcnt lgkmcnt(2)
	v_cvt_pk_bf16_f32 v28, v38, v40
	s_waitcnt lgkmcnt(0)
	v_cvt_pk_bf16_f32 v29, v56, v58
	v_lshl_add_u64 v[62:63], v[60:61], 0, v[62:63]
	v_or_b32_e32 v30, s10, v45
	global_store_dwordx4 v[62:63], v[26:29], off
	s_nop 1
	v_cvt_pk_bf16_f32 v26, v33, v31
	v_ashrrev_i32_e32 v31, 31, v30
	v_cvt_pk_bf16_f32 v27, v35, v37
	v_cvt_pk_bf16_f32 v28, v39, v41
	v_cvt_pk_bf16_f32 v29, v57, v59
	v_lshlrev_b64 v[30:31], 11, v[30:31]
	ds_read2_b32 v[32:33], v44 offset0:49 offset1:57
	ds_read2_b32 v[34:35], v44 offset0:16 offset1:24
	ds_read2_b32 v[36:37], v44 offset0:82 offset1:90
	ds_read2_b32 v[38:39], v44 offset0:115 offset1:123
	ds_read2_b32 v[40:41], v44 offset0:148 offset1:156
	ds_read2_b32 v[56:57], v44 offset0:181 offset1:189
	ds_read2_b32 v[58:59], v44 offset0:214 offset1:222
	ds_read2_b32 v[62:63], v44 offset0:247 offset1:255
	v_lshl_add_u64 v[30:31], v[60:61], 0, v[30:31]
	global_store_dwordx4 v[30:31], v[26:29], off
	v_or_b32_e32 v30, s10, v46
	v_ashrrev_i32_e32 v31, 31, v30
	v_lshlrev_b64 v[30:31], 11, v[30:31]
	s_waitcnt lgkmcnt(6)
	v_cvt_pk_bf16_f32 v26, v34, v32
	s_waitcnt lgkmcnt(4)
	v_cvt_pk_bf16_f32 v27, v36, v38
	s_waitcnt lgkmcnt(2)
	v_cvt_pk_bf16_f32 v28, v40, v56
	s_waitcnt lgkmcnt(0)
	v_cvt_pk_bf16_f32 v29, v58, v62
	v_lshl_add_u64 v[30:31], v[60:61], 0, v[30:31]
	global_store_dwordx4 v[30:31], v[26:29], off
	v_or_b32_e32 v30, s10, v47
	v_ashrrev_i32_e32 v31, 31, v30
	v_lshlrev_b64 v[30:31], 11, v[30:31]
	v_cvt_pk_bf16_f32 v26, v35, v33
	v_cvt_pk_bf16_f32 v27, v37, v39
	v_cvt_pk_bf16_f32 v28, v41, v57
	v_cvt_pk_bf16_f32 v29, v59, v63
	v_lshl_add_u64 v[30:31], v[60:61], 0, v[30:31]
	global_store_dwordx4 v[30:31], v[26:29], off
	s_waitcnt lgkmcnt(0)
	s_branch .LBB0_655

; __global__ void __launch_bounds__(512, 2) mega(Args a) {
;     ...
;                 const float* pr = ka->in[1] + (size_t)l * T * PLE; bf16* pb = (bf16*)(ws + WS_PB2);
;                 for (size_t i = (size_t)bid * 512 + tid; i < (size_t)T * PLE / 8; i += (size_t)gridDim.x * 512) { const f32x4 a = __builtin_nontemporal_load((const f32x4*)(pr + 8 * i)), b = __builtin_nontemporal_load((const f32x4*)(pr + 8 * i + 4)); st8bf(pb + 8 * i, a, b); }
.LBB0_720:
	s_mov_b64 s[0:1], 0x400000
	global_load_dwordx4 v[6:9], v[2:3], off offset:-16 nt
	global_load_dwordx4 v[10:13], v[2:3], off nt
	v_lshl_add_u64 v[2:3], v[2:3], 0, s[0:1]
	global_load_dwordx4 v[14:17], v[2:3], off offset:-16 nt
	global_load_dwordx4 v[18:21], v[2:3], off nt
	v_lshl_add_u64 v[2:3], v[2:3], 0, s[0:1]
	global_load_dwordx4 v[22:25], v[2:3], off offset:-16 nt
	global_load_dwordx4 v[26:29], v[2:3], off nt
	v_lshl_add_u64 v[2:3], v[2:3], 0, s[0:1]
	global_load_dwordx4 v[30:33], v[2:3], off offset:-16 nt
	global_load_dwordx4 v[34:37], v[2:3], off nt
	v_lshl_add_u64 v[2:3], v[2:3], 0, s[0:1]
	global_load_dwordx4 v[38:41], v[2:3], off offset:-16 nt
	global_load_dwordx4 v[42:45], v[2:3], off nt
	v_lshl_add_u64 v[2:3], v[2:3], 0, s[0:1]
	global_load_dwordx4 v[46:49], v[2:3], off offset:-16 nt
	global_load_dwordx4 v[50:53], v[2:3], off nt
	v_lshl_add_u64 v[2:3], v[2:3], 0, s[0:1]
	global_load_dwordx4 v[54:57], v[2:3], off offset:-16 nt
	global_load_dwordx4 v[58:61], v[2:3], off nt
	v_lshl_add_u64 v[2:3], v[2:3], 0, s[0:1]
	global_load_dwordx4 v[62:65], v[2:3], off offset:-16 nt
	global_load_dwordx4 v[66:69], v[2:3], off nt
	s_waitcnt vmcnt(14)
	v_cvt_pk_bf16_f32 v6, v6, v7
	v_cvt_pk_bf16_f32 v7, v8, v9
	v_cvt_pk_bf16_f32 v8, v10, v11
	v_cvt_pk_bf16_f32 v9, v12, v13
	global_store_dwordx4 v[4:5], v[6:9], off
	v_lshl_add_u64 v[4:5], v[4:5], 0, s[22:23]
	s_waitcnt vmcnt(13)
	v_cvt_pk_bf16_f32 v14, v14, v15
	v_cvt_pk_bf16_f32 v15, v16, v17
	v_cvt_pk_bf16_f32 v16, v18, v19
	v_cvt_pk_bf16_f32 v17, v20, v21
	global_store_dwordx4 v[4:5], v[14:17], off
	v_lshl_add_u64 v[4:5], v[4:5], 0, s[22:23]
	s_waitcnt vmcnt(12)
	v_cvt_pk_bf16_f32 v22, v22, v23
	v_cvt_pk_bf16_f32 v23, v24, v25
	v_cvt_pk_bf16_f32 v24, v26, v27
	v_cvt_pk_bf16_f32 v25, v28, v29
	global_store_dwordx4 v[4:5], v[22:25], off
	v_lshl_add_u64 v[4:5], v[4:5], 0, s[22:23]
	s_waitcnt vmcnt(11)
	v_cvt_pk_bf16_f32 v30, v30, v31
	v_cvt_pk_bf16_f32 v31, v32, v33
	v_cvt_pk_bf16_f32 v32, v34, v35
	v_cvt_pk_bf16_f32 v33, v36, v37
	global_store_dwordx4 v[4:5], v[30:33], off
	v_lshl_add_u64 v[4:5], v[4:5], 0, s[22:23]
	s_waitcnt vmcnt(10)
	v_cvt_pk_bf16_f32 v38, v38, v39
	v_cvt_pk_bf16_f32 v39, v40, v41
	v_cvt_pk_bf16_f32 v40, v42, v43
	v_cvt_pk_bf16_f32 v41, v44, v45
	global_store_dwordx4 v[4:5], v[38:41], off
	v_lshl_add_u64 v[4:5], v[4:5], 0, s[22:23]
	s_waitcnt vmcnt(9)
	v_cvt_pk_bf16_f32 v46, v46, v47
	v_cvt_pk_bf16_f32 v47, v48, v49
	v_cvt_pk_bf16_f32 v48, v50, v51
	v_cvt_pk_bf16_f32 v49, v52, v53
	global_store_dwordx4 v[4:5], v[46:49], off
	v_lshl_add_u64 v[4:5], v[4:5], 0, s[22:23]
	s_waitcnt vmcnt(8)
	v_cvt_pk_bf16_f32 v54, v54, v55
	v_cvt_pk_bf16_f32 v55, v56, v57
	v_cvt_pk_bf16_f32 v56, v58, v59
	v_cvt_pk_bf16_f32 v57, v60, v61
	global_store_dwordx4 v[4:5], v[54:57], off
	v_lshl_add_u64 v[4:5], v[4:5], 0, s[22:23]
	s_waitcnt vmcnt(7)
	v_cvt_pk_bf16_f32 v62, v62, v63
	v_cvt_pk_bf16_f32 v63, v64, v65
	v_cvt_pk_bf16_f32 v64, v66, v67
	v_cvt_pk_bf16_f32 v65, v68, v69
	global_store_dwordx4 v[4:5], v[62:65], off
